# EpiIn epilogue rewritten: per-tile type dispatch, hoisted ssq, pipelined rope loads, gn_g once, no hazard nops
# speedup vs baseline: 1.0486x; 1.0087x over previous
.LBB0_260:
	s_add_u32 s6, s4, 0xfffc0080
	s_addc_u32 s7, s5, -1
	s_add_i32 s35, 0, 0x10000
	s_cmp_eq_u32 s34, 12
	s_cselect_b32 s11, s21, s7
	s_cselect_b32 s10, s26, s6
	v_add_u32_e32 v146, s35, v139
	s_cselect_b32 s7, s19, s29
	s_cselect_b32 s6, s27, s28
	s_add_i32 s92, 0, 0x14000
	ds_read_b128 v[148:151], v146
	ds_read_b128 v[152:155], v146 offset:1024
	ds_read_b128 v[156:159], v146 offset:2048
	ds_read_b128 v[160:163], v146 offset:3072
	v_add_u32_e32 v146, s92, v139
	ds_read_b128 v[170:173], v146
	ds_read_b128 v[174:177], v146 offset:1024
	ds_read_b128 v[178:181], v146 offset:2048
	ds_read_b128 v[182:185], v146 offset:3072
	v_lshl_add_u64 v[206:207], s[4:5], 0, v[142:143]
	s_add_i32 m0, s40, 0xc000
	ds_read_b128 v[186:189], v168
	ds_read_b128 v[190:193], v168 offset:1024
	ds_read_b128 v[194:197], v168 offset:2048
	ds_read_b128 v[198:201], v168 offset:3072
	ds_read_b128 v[202:205], v168 offset:4096
	ds_read_b128 v[222:225], v168 offset:5120
	ds_read_b128 v[236:239], v168 offset:6144
	ds_read_b128 v[240:243], v168 offset:7168
	global_load_lds_dwordx4 v[206:207], off
	v_lshl_add_u64 v[206:207], s[4:5], 0, v[144:145]
	s_add_i32 m0, s40, 0xe000
	s_nop 0
	global_load_lds_dwordx4 v[206:207], off
	s_waitcnt vmcnt(8)
	s_waitcnt lgkmcnt(0)
	s_barrier
	s_setprio 1
	s_waitcnt lgkmcnt(0)
	v_mfma_f32_16x16x32_bf16 v[124:127], v[148:151], v[186:189], v[124:127]
	v_mfma_f32_16x16x32_bf16 v[120:123], v[156:159], v[186:189], v[120:123]
	v_mfma_f32_16x16x32_bf16 v[108:111], v[148:151], v[194:197], v[108:111]
	v_mfma_f32_16x16x32_bf16 v[104:107], v[156:159], v[194:197], v[104:107]
	v_mfma_f32_16x16x32_bf16 v[92:95], v[148:151], v[202:205], v[92:95]
	v_mfma_f32_16x16x32_bf16 v[88:91], v[156:159], v[202:205], v[88:91]
	v_mfma_f32_16x16x32_bf16 v[76:79], v[148:151], v[236:239], v[76:79]
	v_mfma_f32_16x16x32_bf16 v[72:75], v[156:159], v[236:239], v[72:75]
	v_mfma_f32_16x16x32_bf16 v[124:127], v[152:155], v[190:193], v[124:127]
	v_mfma_f32_16x16x32_bf16 v[120:123], v[160:163], v[190:193], v[120:123]
	v_mfma_f32_16x16x32_bf16 v[108:111], v[152:155], v[198:201], v[108:111]
	v_mfma_f32_16x16x32_bf16 v[104:107], v[160:163], v[198:201], v[104:107]
	v_mfma_f32_16x16x32_bf16 v[92:95], v[152:155], v[222:225], v[92:95]
	v_mfma_f32_16x16x32_bf16 v[88:91], v[160:163], v[222:225], v[88:91]
	v_mfma_f32_16x16x32_bf16 v[76:79], v[152:155], v[240:243], v[76:79]
	v_mfma_f32_16x16x32_bf16 v[72:75], v[160:163], v[240:243], v[72:75]
	s_setprio 0
	s_setprio 1
	v_mfma_f32_16x16x32_bf16 v[116:119], v[170:173], v[186:189], v[116:119]
	v_mfma_f32_16x16x32_bf16 v[112:115], v[178:181], v[186:189], v[112:115]
	v_mfma_f32_16x16x32_bf16 v[100:103], v[170:173], v[194:197], v[100:103]
	v_mfma_f32_16x16x32_bf16 v[96:99], v[178:181], v[194:197], v[96:99]
	v_mfma_f32_16x16x32_bf16 v[84:87], v[170:173], v[202:205], v[84:87]
	v_mfma_f32_16x16x32_bf16 v[80:83], v[178:181], v[202:205], v[80:83]
	v_mfma_f32_16x16x32_bf16 v[68:71], v[170:173], v[236:239], v[68:71]
	v_mfma_f32_16x16x32_bf16 v[64:67], v[178:181], v[236:239], v[64:67]
	v_mfma_f32_16x16x32_bf16 v[116:119], v[174:177], v[190:193], v[116:119]
	v_mfma_f32_16x16x32_bf16 v[112:115], v[182:185], v[190:193], v[112:115]
	v_mfma_f32_16x16x32_bf16 v[100:103], v[174:177], v[198:201], v[100:103]
	v_mfma_f32_16x16x32_bf16 v[96:99], v[182:185], v[198:201], v[96:99]
	v_mfma_f32_16x16x32_bf16 v[84:87], v[174:177], v[222:225], v[84:87]
	v_mfma_f32_16x16x32_bf16 v[80:83], v[182:185], v[222:225], v[80:83]
	v_mfma_f32_16x16x32_bf16 v[68:71], v[174:177], v[240:243], v[68:71]
	v_mfma_f32_16x16x32_bf16 v[64:67], v[182:185], v[240:243], v[64:67]
	s_setprio 0
	s_barrier
	s_add_i32 s35, s35, s37
	v_lshl_add_u64 v[206:207], s[6:7], 0, v[132:133]
	s_mov_b32 m0, s35
	ds_read_b128 v[186:189], v168 offset:16384
	ds_read_b128 v[190:193], v168 offset:17408
	ds_read_b128 v[194:197], v168 offset:18432
	ds_read_b128 v[198:201], v168 offset:19456
	ds_read_b128 v[202:205], v168 offset:20480
	ds_read_b128 v[222:225], v168 offset:21504
	ds_read_b128 v[236:239], v168 offset:22528
	ds_read_b128 v[240:243], v168 offset:23552
	global_load_lds_dwordx4 v[206:207], off
	s_add_i32 m0, s35, 0x2000
	s_add_u32 vcc_lo, s6, 0x40000
	v_lshl_add_u64 v[244:245], s[6:7], 0, v[128:129]
	s_addc_u32 vcc_hi, s7, 0
	s_add_i32 s35, s92, s37
	global_load_lds_dwordx4 v[244:245], off
	v_lshl_add_u64 v[246:247], vcc, 0, v[132:133]
	s_mov_b32 m0, s35
	v_lshl_add_u64 v[248:249], s[10:11], 0, v[130:131]
	global_load_lds_dwordx4 v[246:247], off
	v_lshl_add_u64 v[246:247], vcc, 0, v[128:129]
	s_add_i32 m0, s35, 0x2000
	s_nop 0
	global_load_lds_dwordx4 v[246:247], off
	v_lshl_add_u64 v[246:247], s[10:11], 0, v[134:135]
	s_mov_b32 m0, s40
	s_nop 0
	global_load_lds_dwordx4 v[246:247], off
	s_mov_b32 m0, s41
	s_nop 0
	global_load_lds_dwordx4 v[248:249], off
	s_waitcnt vmcnt(8)
	s_waitcnt lgkmcnt(0)
	s_barrier
	s_setprio 1
	s_waitcnt lgkmcnt(0)
	v_mfma_f32_16x16x32_bf16 v[60:63], v[148:151], v[186:189], v[60:63]
	v_mfma_f32_16x16x32_bf16 v[56:59], v[156:159], v[186:189], v[56:59]
	v_mfma_f32_16x16x32_bf16 v[44:47], v[148:151], v[194:197], v[44:47]
	v_mfma_f32_16x16x32_bf16 v[40:43], v[156:159], v[194:197], v[40:43]
	v_mfma_f32_16x16x32_bf16 v[28:31], v[148:151], v[202:205], v[28:31]
	v_mfma_f32_16x16x32_bf16 v[24:27], v[156:159], v[202:205], v[24:27]
	v_mfma_f32_16x16x32_bf16 v[12:15], v[148:151], v[236:239], v[12:15]
	v_mfma_f32_16x16x32_bf16 v[8:11], v[156:159], v[236:239], v[8:11]
	v_mfma_f32_16x16x32_bf16 v[60:63], v[152:155], v[190:193], v[60:63]
	v_mfma_f32_16x16x32_bf16 v[56:59], v[160:163], v[190:193], v[56:59]
	v_mfma_f32_16x16x32_bf16 v[44:47], v[152:155], v[198:201], v[44:47]
	v_mfma_f32_16x16x32_bf16 v[40:43], v[160:163], v[198:201], v[40:43]
	v_mfma_f32_16x16x32_bf16 v[28:31], v[152:155], v[222:225], v[28:31]
	v_mfma_f32_16x16x32_bf16 v[24:27], v[160:163], v[222:225], v[24:27]
	v_mfma_f32_16x16x32_bf16 v[12:15], v[152:155], v[240:243], v[12:15]
	v_mfma_f32_16x16x32_bf16 v[8:11], v[160:163], v[240:243], v[8:11]
	s_setprio 0
	s_setprio 1
	v_mfma_f32_16x16x32_bf16 v[52:55], v[170:173], v[186:189], v[52:55]
	v_mfma_f32_16x16x32_bf16 v[48:51], v[178:181], v[186:189], v[48:51]
	v_mfma_f32_16x16x32_bf16 v[36:39], v[170:173], v[194:197], v[36:39]
	v_mfma_f32_16x16x32_bf16 v[32:35], v[178:181], v[194:197], v[32:35]
	v_mfma_f32_16x16x32_bf16 v[20:23], v[170:173], v[202:205], v[20:23]
	v_mfma_f32_16x16x32_bf16 v[16:19], v[178:181], v[202:205], v[16:19]
	v_mfma_f32_16x16x32_bf16 v[4:7], v[170:173], v[236:239], v[4:7]
	v_mfma_f32_16x16x32_bf16 v[0:3], v[178:181], v[236:239], v[0:3]
	v_mfma_f32_16x16x32_bf16 v[52:55], v[174:177], v[190:193], v[52:55]
	v_mfma_f32_16x16x32_bf16 v[48:51], v[182:185], v[190:193], v[48:51]
	v_mfma_f32_16x16x32_bf16 v[36:39], v[174:177], v[198:201], v[36:39]
	v_mfma_f32_16x16x32_bf16 v[32:35], v[182:185], v[198:201], v[32:35]
	v_mfma_f32_16x16x32_bf16 v[20:23], v[174:177], v[222:225], v[20:23]
	v_mfma_f32_16x16x32_bf16 v[16:19], v[182:185], v[222:225], v[16:19]
	v_mfma_f32_16x16x32_bf16 v[4:7], v[174:177], v[240:243], v[4:7]
	v_mfma_f32_16x16x32_bf16 v[0:3], v[182:185], v[240:243], v[0:3]
	s_setprio 0
	s_barrier
	s_add_i32 s35, 0, 0x18000
	v_add_u32_e32 v146, s35, v139
	s_add_i32 s92, 0, 0x1c000
	ds_read_b128 v[148:151], v146
	ds_read_b128 v[152:155], v146 offset:1024
	ds_read_b128 v[156:159], v146 offset:2048
	ds_read_b128 v[160:163], v146 offset:3072
	v_add_u32_e32 v146, s92, v139
	ds_read_b128 v[170:173], v146
	ds_read_b128 v[174:177], v146 offset:1024
	ds_read_b128 v[178:181], v146 offset:2048
	ds_read_b128 v[182:185], v146 offset:3072
	s_add_u32 s10, s10, 0x40000
	s_addc_u32 s11, s11, 0
	s_mov_b32 m0, s42
	v_lshl_add_u64 v[250:251], s[10:11], 0, v[134:135]
	ds_read_b128 v[186:189], v168 offset:32768
	ds_read_b128 v[190:193], v168 offset:33792
	ds_read_b128 v[194:197], v168 offset:34816
	ds_read_b128 v[198:201], v168 offset:35840
	ds_read_b128 v[202:205], v168 offset:36864
	ds_read_b128 v[222:225], v168 offset:37888
	ds_read_b128 v[236:239], v168 offset:38912
	ds_read_b128 v[240:243], v168 offset:39936
	global_load_lds_dwordx4 v[250:251], off
	v_lshl_add_u64 v[250:251], s[10:11], 0, v[130:131]
	s_mov_b32 m0, s43
	s_nop 0
	global_load_lds_dwordx4 v[250:251], off
	s_waitcnt vmcnt(8)
	s_waitcnt lgkmcnt(0)
	s_barrier
	s_setprio 1
	s_waitcnt lgkmcnt(0)
	v_mfma_f32_16x16x32_bf16 v[124:127], v[148:151], v[186:189], v[124:127]
	v_mfma_f32_16x16x32_bf16 v[120:123], v[156:159], v[186:189], v[120:123]
	v_mfma_f32_16x16x32_bf16 v[108:111], v[148:151], v[194:197], v[108:111]
	v_mfma_f32_16x16x32_bf16 v[104:107], v[156:159], v[194:197], v[104:107]
	v_mfma_f32_16x16x32_bf16 v[92:95], v[148:151], v[202:205], v[92:95]
	v_mfma_f32_16x16x32_bf16 v[88:91], v[156:159], v[202:205], v[88:91]
	v_mfma_f32_16x16x32_bf16 v[76:79], v[148:151], v[236:239], v[76:79]
	v_mfma_f32_16x16x32_bf16 v[72:75], v[156:159], v[236:239], v[72:75]
	v_mfma_f32_16x16x32_bf16 v[124:127], v[152:155], v[190:193], v[124:127]
	v_mfma_f32_16x16x32_bf16 v[120:123], v[160:163], v[190:193], v[120:123]
	v_mfma_f32_16x16x32_bf16 v[108:111], v[152:155], v[198:201], v[108:111]
	v_mfma_f32_16x16x32_bf16 v[104:107], v[160:163], v[198:201], v[104:107]
	v_mfma_f32_16x16x32_bf16 v[92:95], v[152:155], v[222:225], v[92:95]
	v_mfma_f32_16x16x32_bf16 v[88:91], v[160:163], v[222:225], v[88:91]
	v_mfma_f32_16x16x32_bf16 v[76:79], v[152:155], v[240:243], v[76:79]
	v_mfma_f32_16x16x32_bf16 v[72:75], v[160:163], v[240:243], v[72:75]
	s_setprio 0
	s_setprio 1
	v_mfma_f32_16x16x32_bf16 v[116:119], v[170:173], v[186:189], v[116:119]
	v_mfma_f32_16x16x32_bf16 v[112:115], v[178:181], v[186:189], v[112:115]
	v_mfma_f32_16x16x32_bf16 v[100:103], v[170:173], v[194:197], v[100:103]
	v_mfma_f32_16x16x32_bf16 v[96:99], v[178:181], v[194:197], v[96:99]
	v_mfma_f32_16x16x32_bf16 v[84:87], v[170:173], v[202:205], v[84:87]
	v_mfma_f32_16x16x32_bf16 v[80:83], v[178:181], v[202:205], v[80:83]
	v_mfma_f32_16x16x32_bf16 v[68:71], v[170:173], v[236:239], v[68:71]
	v_mfma_f32_16x16x32_bf16 v[64:67], v[178:181], v[236:239], v[64:67]
	v_mfma_f32_16x16x32_bf16 v[116:119], v[174:177], v[190:193], v[116:119]
	v_mfma_f32_16x16x32_bf16 v[112:115], v[182:185], v[190:193], v[112:115]
	v_mfma_f32_16x16x32_bf16 v[100:103], v[174:177], v[198:201], v[100:103]
	v_mfma_f32_16x16x32_bf16 v[96:99], v[182:185], v[198:201], v[96:99]
	v_mfma_f32_16x16x32_bf16 v[84:87], v[174:177], v[222:225], v[84:87]
	v_mfma_f32_16x16x32_bf16 v[80:83], v[182:185], v[222:225], v[80:83]
	v_mfma_f32_16x16x32_bf16 v[68:71], v[174:177], v[240:243], v[68:71]
	v_mfma_f32_16x16x32_bf16 v[64:67], v[182:185], v[240:243], v[64:67]
	s_setprio 0
	s_barrier
	s_add_i32 s10, s35, s37
	v_lshl_add_u64 v[206:207], v[206:207], 0, s[94:95]
	s_mov_b32 m0, s10
	ds_read_b128 v[186:189], v168 offset:49152
	ds_read_b128 v[190:193], v168 offset:50176
	ds_read_b128 v[194:197], v168 offset:51200
	ds_read_b128 v[198:201], v168 offset:52224
	ds_read_b128 v[202:205], v168 offset:53248
	ds_read_b128 v[222:225], v168 offset:54272
	ds_read_b128 v[236:239], v168 offset:55296
	ds_read_b128 v[240:243], v168 offset:56320
	global_load_lds_dwordx4 v[206:207], off
	s_add_i32 m0, s10, 0x2000
	s_add_u32 s6, s6, 0x40080
	v_lshl_add_u64 v[206:207], v[244:245], 0, s[94:95]
	s_addc_u32 s7, s7, 0
	s_add_i32 s10, s92, s37
	global_load_lds_dwordx4 v[206:207], off
	v_lshl_add_u64 v[206:207], s[6:7], 0, v[132:133]
	s_mov_b32 m0, s10
	s_nop 0
	global_load_lds_dwordx4 v[206:207], off
	v_lshl_add_u64 v[206:207], s[6:7], 0, v[128:129]
	s_add_i32 m0, s10, 0x2000
	s_nop 0
	global_load_lds_dwordx4 v[206:207], off
	v_lshl_add_u64 v[206:207], v[246:247], 0, s[94:95]
	s_mov_b32 m0, s76
	s_nop 0
	global_load_lds_dwordx4 v[206:207], off
	v_lshl_add_u64 v[206:207], v[248:249], 0, s[94:95]
	s_mov_b32 m0, s77
	s_nop 0
	global_load_lds_dwordx4 v[206:207], off
	s_waitcnt vmcnt(8)
	s_waitcnt lgkmcnt(0)
	s_barrier
	s_setprio 1
	s_waitcnt lgkmcnt(0)
	v_mfma_f32_16x16x32_bf16 v[60:63], v[148:151], v[186:189], v[60:63]
	v_mfma_f32_16x16x32_bf16 v[56:59], v[156:159], v[186:189], v[56:59]
	v_mfma_f32_16x16x32_bf16 v[44:47], v[148:151], v[194:197], v[44:47]
	v_mfma_f32_16x16x32_bf16 v[40:43], v[156:159], v[194:197], v[40:43]
	v_mfma_f32_16x16x32_bf16 v[28:31], v[148:151], v[202:205], v[28:31]
	v_mfma_f32_16x16x32_bf16 v[24:27], v[156:159], v[202:205], v[24:27]
	v_mfma_f32_16x16x32_bf16 v[12:15], v[148:151], v[236:239], v[12:15]
	v_mfma_f32_16x16x32_bf16 v[8:11], v[156:159], v[236:239], v[8:11]
	v_mfma_f32_16x16x32_bf16 v[60:63], v[152:155], v[190:193], v[60:63]
	v_mfma_f32_16x16x32_bf16 v[56:59], v[160:163], v[190:193], v[56:59]
	v_mfma_f32_16x16x32_bf16 v[44:47], v[152:155], v[198:201], v[44:47]
	v_mfma_f32_16x16x32_bf16 v[40:43], v[160:163], v[198:201], v[40:43]
	v_mfma_f32_16x16x32_bf16 v[28:31], v[152:155], v[222:225], v[28:31]
	v_mfma_f32_16x16x32_bf16 v[24:27], v[160:163], v[222:225], v[24:27]
	v_mfma_f32_16x16x32_bf16 v[12:15], v[152:155], v[240:243], v[12:15]
	v_mfma_f32_16x16x32_bf16 v[8:11], v[160:163], v[240:243], v[8:11]
	s_setprio 0
	s_setprio 1
	v_mfma_f32_16x16x32_bf16 v[52:55], v[170:173], v[186:189], v[52:55]
	v_mfma_f32_16x16x32_bf16 v[48:51], v[178:181], v[186:189], v[48:51]
	v_mfma_f32_16x16x32_bf16 v[36:39], v[170:173], v[194:197], v[36:39]
	v_mfma_f32_16x16x32_bf16 v[32:35], v[178:181], v[194:197], v[32:35]
	v_mfma_f32_16x16x32_bf16 v[20:23], v[170:173], v[202:205], v[20:23]
	v_mfma_f32_16x16x32_bf16 v[16:19], v[178:181], v[202:205], v[16:19]
	v_mfma_f32_16x16x32_bf16 v[4:7], v[170:173], v[236:239], v[4:7]
	v_mfma_f32_16x16x32_bf16 v[0:3], v[178:181], v[236:239], v[0:3]
	v_mfma_f32_16x16x32_bf16 v[52:55], v[174:177], v[190:193], v[52:55]
	v_mfma_f32_16x16x32_bf16 v[48:51], v[182:185], v[190:193], v[48:51]
	v_mfma_f32_16x16x32_bf16 v[36:39], v[174:177], v[198:201], v[36:39]
	v_mfma_f32_16x16x32_bf16 v[32:35], v[182:185], v[198:201], v[32:35]
	v_mfma_f32_16x16x32_bf16 v[20:23], v[174:177], v[222:225], v[20:23]
	v_mfma_f32_16x16x32_bf16 v[16:19], v[182:185], v[222:225], v[16:19]
	v_mfma_f32_16x16x32_bf16 v[4:7], v[174:177], v[240:243], v[4:7]
	v_mfma_f32_16x16x32_bf16 v[0:3], v[182:185], v[240:243], v[0:3]
	s_setprio 0
	s_barrier
	s_add_i32 s34, s34, 2
	s_add_u32 s4, s4, 0x100
	s_addc_u32 s5, s5, 0
	s_add_u32 s28, s28, 0x100
	s_addc_u32 s29, s29, 0
	s_cmp_gt_u32 s34, 13
	s_cbranch_scc0 .LBB0_260
	v_and_b32_e32 v148, 15, v226
	v_bfe_u32 v149, v226, 4, 2
	v_bfe_u32 v150, v226, 6, 2
	v_lshrrev_b32_e32 v151, 8, v226
	v_lshl_add_u32 v152, v151, 6, v148
	v_lshlrev_b32_e32 v153, 2, v152
	s_lshl_b32 s4, s31, 10
	s_add_u32 s100, s96, s4
	s_addc_u32 s101, s97, 0
	global_load_dword v154, v153, s[100:101]
	global_load_dword v155, v153, s[100:101] offset:64
	global_load_dword v156, v153, s[100:101] offset:128
	global_load_dword v157, v153, s[100:101] offset:192
	global_load_dword v158, v153, s[100:101] offset:512
	global_load_dword v159, v153, s[100:101] offset:576
	global_load_dword v160, v153, s[100:101] offset:640
	global_load_dword v161, v153, s[100:101] offset:704
	s_and_b64 vcc, exec, s[16:17]
	s_cbranch_vccz .LBB0_263
	s_barrier
.LBB0_263:
	v_mov_b32_e32 v236, 0x358637bd
	s_mov_b32 s4, 0xbfb8aa3b
	s_mov_b32 s5, s4
	s_lshl_b32 s6, s31, 18
	v_lshlrev_b32_e32 v162, 10, v152
	s_waitcnt vmcnt(0)
	v_fmamk_f32 v154, v154, 0x3a800000, v236
	v_fmamk_f32 v155, v155, 0x3a800000, v236
	v_fmamk_f32 v156, v156, 0x3a800000, v236
	v_fmamk_f32 v157, v157, 0x3a800000, v236
	v_fmamk_f32 v158, v158, 0x3a800000, v236
	v_fmamk_f32 v159, v159, 0x3a800000, v236
	v_fmamk_f32 v160, v160, 0x3a800000, v236
	v_fmamk_f32 v161, v161, 0x3a800000, v236
	v_rsq_f32_e32 v154, v154
	v_rsq_f32_e32 v155, v155
	v_rsq_f32_e32 v156, v156
	v_rsq_f32_e32 v157, v157
	v_rsq_f32_e32 v158, v158
	v_rsq_f32_e32 v159, v159
	v_rsq_f32_e32 v160, v160
	v_rsq_f32_e32 v161, v161
	s_cmp_lt_u32 s30, 4
	s_cbranch_scc1 .Lei_glu
	s_cmp_lt_u32 s30, 8
	s_cbranch_scc1 .Lei_rope
	s_cmp_lt_u32 s30, 10
	s_cbranch_scc1 .Lei_v
	s_sub_i32 s7, s30, 10
	v_lshl_add_u32 v163, v150, 5, 0
	v_lshl_add_u32 v163, v149, 3, v163
	v_lshl_add_u32 v162, v163, 1, v162
	v_lshlrev_b32_e32 v163, 2, v163
	s_lshl_b32 s10, s7, 10
	s_add_u32 s98, s12, s10
	s_addc_u32 s99, s13, 0
	global_load_dwordx4 v[170:173], v163, s[98:99]
	global_load_dwordx4 v[174:177], v163, s[98:99] offset:16
	global_load_dwordx4 v[178:181], v163, s[98:99] offset:512
	global_load_dwordx4 v[182:185], v163, s[98:99] offset:528
	s_lshl_b32 s10, s7, 9
	s_add_i32 s10, s10, s6
	s_add_u32 s100, s54, s10
	s_addc_u32 s101, s55, 0
	v_pk_mul_f32 v[124:125], v[124:125], v[154:155] op_sel_hi:[1,0]
	v_pk_mul_f32 v[126:127], v[126:127], v[154:155] op_sel_hi:[1,0]
	v_pk_mul_f32 v[120:121], v[120:121], v[154:155] op_sel_hi:[1,0]
	v_pk_mul_f32 v[122:123], v[122:123], v[154:155] op_sel_hi:[1,0]
	v_pk_mul_f32 v[116:117], v[116:117], v[154:155] op_sel_hi:[1,0]
	v_pk_mul_f32 v[118:119], v[118:119], v[154:155] op_sel_hi:[1,0]
	v_pk_mul_f32 v[112:113], v[112:113], v[154:155] op_sel_hi:[1,0]
	v_pk_mul_f32 v[114:115], v[114:115], v[154:155] op_sel_hi:[1,0]
	v_pk_mul_f32 v[186:187], v[124:125], s[4:5]
	v_pk_mul_f32 v[188:189], v[126:127], s[4:5]
	v_pk_mul_f32 v[190:191], v[120:121], s[4:5]
	v_pk_mul_f32 v[192:193], v[122:123], s[4:5]
	v_pk_mul_f32 v[194:195], v[116:117], s[4:5]
	v_pk_mul_f32 v[196:197], v[118:119], s[4:5]
	v_pk_mul_f32 v[198:199], v[112:113], s[4:5]
	v_pk_mul_f32 v[200:201], v[114:115], s[4:5]
	v_exp_f32_e32 v186, v186
	v_exp_f32_e32 v187, v187
	v_exp_f32_e32 v188, v188
	v_exp_f32_e32 v189, v189
	v_exp_f32_e32 v190, v190
	v_exp_f32_e32 v191, v191
	v_exp_f32_e32 v192, v192
	v_exp_f32_e32 v193, v193
	v_exp_f32_e32 v194, v194
	v_exp_f32_e32 v195, v195
	v_exp_f32_e32 v196, v196
	v_exp_f32_e32 v197, v197
	v_exp_f32_e32 v198, v198
	v_exp_f32_e32 v199, v199
	v_exp_f32_e32 v200, v200
	v_exp_f32_e32 v201, v201
	v_add_f32_e32 v186, 1.0, v186
	v_add_f32_e32 v187, 1.0, v187
	v_add_f32_e32 v188, 1.0, v188
	v_add_f32_e32 v189, 1.0, v189
	v_add_f32_e32 v190, 1.0, v190
	v_add_f32_e32 v191, 1.0, v191
	v_add_f32_e32 v192, 1.0, v192
	v_add_f32_e32 v193, 1.0, v193
	v_add_f32_e32 v194, 1.0, v194
	v_add_f32_e32 v195, 1.0, v195
	v_add_f32_e32 v196, 1.0, v196
	v_add_f32_e32 v197, 1.0, v197
	v_add_f32_e32 v198, 1.0, v198
	v_add_f32_e32 v199, 1.0, v199
	v_add_f32_e32 v200, 1.0, v200
	v_add_f32_e32 v201, 1.0, v201
	v_rcp_f32_e32 v186, v186
	v_rcp_f32_e32 v187, v187
	v_rcp_f32_e32 v188, v188
	v_rcp_f32_e32 v189, v189
	v_rcp_f32_e32 v190, v190
	v_rcp_f32_e32 v191, v191
	v_rcp_f32_e32 v192, v192
	v_rcp_f32_e32 v193, v193
	v_rcp_f32_e32 v194, v194
	v_rcp_f32_e32 v195, v195
	v_rcp_f32_e32 v196, v196
	v_rcp_f32_e32 v197, v197
	v_rcp_f32_e32 v198, v198
	v_rcp_f32_e32 v199, v199
	v_rcp_f32_e32 v200, v200
	v_rcp_f32_e32 v201, v201
	s_waitcnt vmcnt(0)
	v_pk_mul_f32 v[124:125], v[124:125], v[186:187]
	v_pk_mul_f32 v[126:127], v[126:127], v[188:189]
	v_pk_mul_f32 v[120:121], v[120:121], v[190:191]
	v_pk_mul_f32 v[122:123], v[122:123], v[192:193]
	v_pk_mul_f32 v[116:117], v[116:117], v[194:195]
	v_pk_mul_f32 v[118:119], v[118:119], v[196:197]
	v_pk_mul_f32 v[112:113], v[112:113], v[198:199]
	v_pk_mul_f32 v[114:115], v[114:115], v[200:201]
	v_pk_mul_f32 v[124:125], v[124:125], v[170:171]
	v_pk_mul_f32 v[126:127], v[126:127], v[172:173]
	v_pk_mul_f32 v[120:121], v[120:121], v[174:175]
	v_pk_mul_f32 v[122:123], v[122:123], v[176:177]
	v_pk_mul_f32 v[116:117], v[116:117], v[178:179]
	v_pk_mul_f32 v[118:119], v[118:119], v[180:181]
	v_pk_mul_f32 v[112:113], v[112:113], v[182:183]
	v_pk_mul_f32 v[114:115], v[114:115], v[184:185]
	v_cvt_pk_bf16_f32 v124, v124, v125
	v_cvt_pk_bf16_f32 v125, v126, v127
	v_cvt_pk_bf16_f32 v126, v120, v121
	v_cvt_pk_bf16_f32 v127, v122, v123
	v_cvt_pk_bf16_f32 v116, v116, v117
	v_cvt_pk_bf16_f32 v117, v118, v119
	v_cvt_pk_bf16_f32 v118, v112, v113
	v_cvt_pk_bf16_f32 v119, v114, v115
	global_store_dwordx4 v162, v[124:127], s[100:101]
	global_store_dwordx4 v162, v[116:119], s[100:101] offset:256
	s_add_u32 s100, s100, 0x4000
	s_addc_u32 s101, s101, 0
	v_pk_mul_f32 v[108:109], v[108:109], v[154:155] op_sel:[0,1] op_sel_hi:[1,1]
	v_pk_mul_f32 v[110:111], v[110:111], v[154:155] op_sel:[0,1] op_sel_hi:[1,1]
	v_pk_mul_f32 v[104:105], v[104:105], v[154:155] op_sel:[0,1] op_sel_hi:[1,1]
	v_pk_mul_f32 v[106:107], v[106:107], v[154:155] op_sel:[0,1] op_sel_hi:[1,1]
	v_pk_mul_f32 v[100:101], v[100:101], v[154:155] op_sel:[0,1] op_sel_hi:[1,1]
	v_pk_mul_f32 v[102:103], v[102:103], v[154:155] op_sel:[0,1] op_sel_hi:[1,1]
	v_pk_mul_f32 v[96:97], v[96:97], v[154:155] op_sel:[0,1] op_sel_hi:[1,1]
	v_pk_mul_f32 v[98:99], v[98:99], v[154:155] op_sel:[0,1] op_sel_hi:[1,1]
	v_pk_mul_f32 v[186:187], v[108:109], s[4:5]
	v_pk_mul_f32 v[188:189], v[110:111], s[4:5]
	v_pk_mul_f32 v[190:191], v[104:105], s[4:5]
	v_pk_mul_f32 v[192:193], v[106:107], s[4:5]
	v_pk_mul_f32 v[194:195], v[100:101], s[4:5]
	v_pk_mul_f32 v[196:197], v[102:103], s[4:5]
	v_pk_mul_f32 v[198:199], v[96:97], s[4:5]
	v_pk_mul_f32 v[200:201], v[98:99], s[4:5]
	v_exp_f32_e32 v186, v186
	v_exp_f32_e32 v187, v187
	v_exp_f32_e32 v188, v188
	v_exp_f32_e32 v189, v189
	v_exp_f32_e32 v190, v190
	v_exp_f32_e32 v191, v191
	v_exp_f32_e32 v192, v192
	v_exp_f32_e32 v193, v193
	v_exp_f32_e32 v194, v194
	v_exp_f32_e32 v195, v195
	v_exp_f32_e32 v196, v196
	v_exp_f32_e32 v197, v197
	v_exp_f32_e32 v198, v198
	v_exp_f32_e32 v199, v199
	v_exp_f32_e32 v200, v200
	v_exp_f32_e32 v201, v201
	v_add_f32_e32 v186, 1.0, v186
	v_add_f32_e32 v187, 1.0, v187
	v_add_f32_e32 v188, 1.0, v188
	v_add_f32_e32 v189, 1.0, v189
	v_add_f32_e32 v190, 1.0, v190
	v_add_f32_e32 v191, 1.0, v191
	v_add_f32_e32 v192, 1.0, v192
	v_add_f32_e32 v193, 1.0, v193
	v_add_f32_e32 v194, 1.0, v194
	v_add_f32_e32 v195, 1.0, v195
	v_add_f32_e32 v196, 1.0, v196
	v_add_f32_e32 v197, 1.0, v197
	v_add_f32_e32 v198, 1.0, v198
	v_add_f32_e32 v199, 1.0, v199
	v_add_f32_e32 v200, 1.0, v200
	v_add_f32_e32 v201, 1.0, v201
	v_rcp_f32_e32 v186, v186
	v_rcp_f32_e32 v187, v187
	v_rcp_f32_e32 v188, v188
	v_rcp_f32_e32 v189, v189
	v_rcp_f32_e32 v190, v190
	v_rcp_f32_e32 v191, v191
	v_rcp_f32_e32 v192, v192
	v_rcp_f32_e32 v193, v193
	v_rcp_f32_e32 v194, v194
	v_rcp_f32_e32 v195, v195
	v_rcp_f32_e32 v196, v196
	v_rcp_f32_e32 v197, v197
	v_rcp_f32_e32 v198, v198
	v_rcp_f32_e32 v199, v199
	v_rcp_f32_e32 v200, v200
	v_rcp_f32_e32 v201, v201
	v_pk_mul_f32 v[108:109], v[108:109], v[186:187]
	v_pk_mul_f32 v[110:111], v[110:111], v[188:189]
	v_pk_mul_f32 v[104:105], v[104:105], v[190:191]
	v_pk_mul_f32 v[106:107], v[106:107], v[192:193]
	v_pk_mul_f32 v[100:101], v[100:101], v[194:195]
	v_pk_mul_f32 v[102:103], v[102:103], v[196:197]
	v_pk_mul_f32 v[96:97], v[96:97], v[198:199]
	v_pk_mul_f32 v[98:99], v[98:99], v[200:201]
	v_pk_mul_f32 v[108:109], v[108:109], v[170:171]
	v_pk_mul_f32 v[110:111], v[110:111], v[172:173]
	v_pk_mul_f32 v[104:105], v[104:105], v[174:175]
	v_pk_mul_f32 v[106:107], v[106:107], v[176:177]
	v_pk_mul_f32 v[100:101], v[100:101], v[178:179]
	v_pk_mul_f32 v[102:103], v[102:103], v[180:181]
	v_pk_mul_f32 v[96:97], v[96:97], v[182:183]
	v_pk_mul_f32 v[98:99], v[98:99], v[184:185]
	v_cvt_pk_bf16_f32 v108, v108, v109
	v_cvt_pk_bf16_f32 v109, v110, v111
	v_cvt_pk_bf16_f32 v110, v104, v105
	v_cvt_pk_bf16_f32 v111, v106, v107
	v_cvt_pk_bf16_f32 v100, v100, v101
	v_cvt_pk_bf16_f32 v101, v102, v103
	v_cvt_pk_bf16_f32 v102, v96, v97
	v_cvt_pk_bf16_f32 v103, v98, v99
	global_store_dwordx4 v162, v[108:111], s[100:101]
	global_store_dwordx4 v162, v[100:103], s[100:101] offset:256
	s_add_u32 s100, s100, 0x4000
	s_addc_u32 s101, s101, 0
	v_pk_mul_f32 v[92:93], v[92:93], v[156:157] op_sel_hi:[1,0]
	v_pk_mul_f32 v[94:95], v[94:95], v[156:157] op_sel_hi:[1,0]
	v_pk_mul_f32 v[88:89], v[88:89], v[156:157] op_sel_hi:[1,0]
	v_pk_mul_f32 v[90:91], v[90:91], v[156:157] op_sel_hi:[1,0]
	v_pk_mul_f32 v[84:85], v[84:85], v[156:157] op_sel_hi:[1,0]
	v_pk_mul_f32 v[86:87], v[86:87], v[156:157] op_sel_hi:[1,0]
	v_pk_mul_f32 v[80:81], v[80:81], v[156:157] op_sel_hi:[1,0]
	v_pk_mul_f32 v[82:83], v[82:83], v[156:157] op_sel_hi:[1,0]
	v_pk_mul_f32 v[186:187], v[92:93], s[4:5]
	v_pk_mul_f32 v[188:189], v[94:95], s[4:5]
	v_pk_mul_f32 v[190:191], v[88:89], s[4:5]
	v_pk_mul_f32 v[192:193], v[90:91], s[4:5]
	v_pk_mul_f32 v[194:195], v[84:85], s[4:5]
	v_pk_mul_f32 v[196:197], v[86:87], s[4:5]
	v_pk_mul_f32 v[198:199], v[80:81], s[4:5]
	v_pk_mul_f32 v[200:201], v[82:83], s[4:5]
	v_exp_f32_e32 v186, v186
	v_exp_f32_e32 v187, v187
	v_exp_f32_e32 v188, v188
	v_exp_f32_e32 v189, v189
	v_exp_f32_e32 v190, v190
	v_exp_f32_e32 v191, v191
	v_exp_f32_e32 v192, v192
	v_exp_f32_e32 v193, v193
	v_exp_f32_e32 v194, v194
	v_exp_f32_e32 v195, v195
	v_exp_f32_e32 v196, v196
	v_exp_f32_e32 v197, v197
	v_exp_f32_e32 v198, v198
	v_exp_f32_e32 v199, v199
	v_exp_f32_e32 v200, v200
	v_exp_f32_e32 v201, v201
	v_add_f32_e32 v186, 1.0, v186
	v_add_f32_e32 v187, 1.0, v187
	v_add_f32_e32 v188, 1.0, v188
	v_add_f32_e32 v189, 1.0, v189
	v_add_f32_e32 v190, 1.0, v190
	v_add_f32_e32 v191, 1.0, v191
	v_add_f32_e32 v192, 1.0, v192
	v_add_f32_e32 v193, 1.0, v193
	v_add_f32_e32 v194, 1.0, v194
	v_add_f32_e32 v195, 1.0, v195
	v_add_f32_e32 v196, 1.0, v196
	v_add_f32_e32 v197, 1.0, v197
	v_add_f32_e32 v198, 1.0, v198
	v_add_f32_e32 v199, 1.0, v199
	v_add_f32_e32 v200, 1.0, v200
	v_add_f32_e32 v201, 1.0, v201
	v_rcp_f32_e32 v186, v186
	v_rcp_f32_e32 v187, v187
	v_rcp_f32_e32 v188, v188
	v_rcp_f32_e32 v189, v189
	v_rcp_f32_e32 v190, v190
	v_rcp_f32_e32 v191, v191
	v_rcp_f32_e32 v192, v192
	v_rcp_f32_e32 v193, v193
	v_rcp_f32_e32 v194, v194
	v_rcp_f32_e32 v195, v195
	v_rcp_f32_e32 v196, v196
	v_rcp_f32_e32 v197, v197
	v_rcp_f32_e32 v198, v198
	v_rcp_f32_e32 v199, v199
	v_rcp_f32_e32 v200, v200
	v_rcp_f32_e32 v201, v201
	v_pk_mul_f32 v[92:93], v[92:93], v[186:187]
	v_pk_mul_f32 v[94:95], v[94:95], v[188:189]
	v_pk_mul_f32 v[88:89], v[88:89], v[190:191]
	v_pk_mul_f32 v[90:91], v[90:91], v[192:193]
	v_pk_mul_f32 v[84:85], v[84:85], v[194:195]
	v_pk_mul_f32 v[86:87], v[86:87], v[196:197]
	v_pk_mul_f32 v[80:81], v[80:81], v[198:199]
	v_pk_mul_f32 v[82:83], v[82:83], v[200:201]
	v_pk_mul_f32 v[92:93], v[92:93], v[170:171]
	v_pk_mul_f32 v[94:95], v[94:95], v[172:173]
	v_pk_mul_f32 v[88:89], v[88:89], v[174:175]
	v_pk_mul_f32 v[90:91], v[90:91], v[176:177]
	v_pk_mul_f32 v[84:85], v[84:85], v[178:179]
	v_pk_mul_f32 v[86:87], v[86:87], v[180:181]
	v_pk_mul_f32 v[80:81], v[80:81], v[182:183]
	v_pk_mul_f32 v[82:83], v[82:83], v[184:185]
	v_cvt_pk_bf16_f32 v92, v92, v93
	v_cvt_pk_bf16_f32 v93, v94, v95
	v_cvt_pk_bf16_f32 v94, v88, v89
	v_cvt_pk_bf16_f32 v95, v90, v91
	v_cvt_pk_bf16_f32 v84, v84, v85
	v_cvt_pk_bf16_f32 v85, v86, v87
	v_cvt_pk_bf16_f32 v86, v80, v81
	v_cvt_pk_bf16_f32 v87, v82, v83
	global_store_dwordx4 v162, v[92:95], s[100:101]
	global_store_dwordx4 v162, v[84:87], s[100:101] offset:256
	s_add_u32 s100, s100, 0x4000
	s_addc_u32 s101, s101, 0
	v_pk_mul_f32 v[76:77], v[76:77], v[156:157] op_sel:[0,1] op_sel_hi:[1,1]
	v_pk_mul_f32 v[78:79], v[78:79], v[156:157] op_sel:[0,1] op_sel_hi:[1,1]
	v_pk_mul_f32 v[72:73], v[72:73], v[156:157] op_sel:[0,1] op_sel_hi:[1,1]
	v_pk_mul_f32 v[74:75], v[74:75], v[156:157] op_sel:[0,1] op_sel_hi:[1,1]
	v_pk_mul_f32 v[68:69], v[68:69], v[156:157] op_sel:[0,1] op_sel_hi:[1,1]
	v_pk_mul_f32 v[70:71], v[70:71], v[156:157] op_sel:[0,1] op_sel_hi:[1,1]
	v_pk_mul_f32 v[64:65], v[64:65], v[156:157] op_sel:[0,1] op_sel_hi:[1,1]
	v_pk_mul_f32 v[66:67], v[66:67], v[156:157] op_sel:[0,1] op_sel_hi:[1,1]
	v_pk_mul_f32 v[186:187], v[76:77], s[4:5]
	v_pk_mul_f32 v[188:189], v[78:79], s[4:5]
	v_pk_mul_f32 v[190:191], v[72:73], s[4:5]
	v_pk_mul_f32 v[192:193], v[74:75], s[4:5]
	v_pk_mul_f32 v[194:195], v[68:69], s[4:5]
	v_pk_mul_f32 v[196:197], v[70:71], s[4:5]
	v_pk_mul_f32 v[198:199], v[64:65], s[4:5]
	v_pk_mul_f32 v[200:201], v[66:67], s[4:5]
	v_exp_f32_e32 v186, v186
	v_exp_f32_e32 v187, v187
	v_exp_f32_e32 v188, v188
	v_exp_f32_e32 v189, v189
	v_exp_f32_e32 v190, v190
	v_exp_f32_e32 v191, v191
	v_exp_f32_e32 v192, v192
	v_exp_f32_e32 v193, v193
	v_exp_f32_e32 v194, v194
	v_exp_f32_e32 v195, v195
	v_exp_f32_e32 v196, v196
	v_exp_f32_e32 v197, v197
	v_exp_f32_e32 v198, v198
	v_exp_f32_e32 v199, v199
	v_exp_f32_e32 v200, v200
	v_exp_f32_e32 v201, v201
	v_add_f32_e32 v186, 1.0, v186
	v_add_f32_e32 v187, 1.0, v187
	v_add_f32_e32 v188, 1.0, v188
	v_add_f32_e32 v189, 1.0, v189
	v_add_f32_e32 v190, 1.0, v190
	v_add_f32_e32 v191, 1.0, v191
	v_add_f32_e32 v192, 1.0, v192
	v_add_f32_e32 v193, 1.0, v193
	v_add_f32_e32 v194, 1.0, v194
	v_add_f32_e32 v195, 1.0, v195
	v_add_f32_e32 v196, 1.0, v196
	v_add_f32_e32 v197, 1.0, v197
	v_add_f32_e32 v198, 1.0, v198
	v_add_f32_e32 v199, 1.0, v199
	v_add_f32_e32 v200, 1.0, v200
	v_add_f32_e32 v201, 1.0, v201
	v_rcp_f32_e32 v186, v186
	v_rcp_f32_e32 v187, v187
	v_rcp_f32_e32 v188, v188
	v_rcp_f32_e32 v189, v189
	v_rcp_f32_e32 v190, v190
	v_rcp_f32_e32 v191, v191
	v_rcp_f32_e32 v192, v192
	v_rcp_f32_e32 v193, v193
	v_rcp_f32_e32 v194, v194
	v_rcp_f32_e32 v195, v195
	v_rcp_f32_e32 v196, v196
	v_rcp_f32_e32 v197, v197
	v_rcp_f32_e32 v198, v198
	v_rcp_f32_e32 v199, v199
	v_rcp_f32_e32 v200, v200
	v_rcp_f32_e32 v201, v201
	v_pk_mul_f32 v[76:77], v[76:77], v[186:187]
	v_pk_mul_f32 v[78:79], v[78:79], v[188:189]
	v_pk_mul_f32 v[72:73], v[72:73], v[190:191]
	v_pk_mul_f32 v[74:75], v[74:75], v[192:193]
	v_pk_mul_f32 v[68:69], v[68:69], v[194:195]
	v_pk_mul_f32 v[70:71], v[70:71], v[196:197]
	v_pk_mul_f32 v[64:65], v[64:65], v[198:199]
	v_pk_mul_f32 v[66:67], v[66:67], v[200:201]
	v_pk_mul_f32 v[76:77], v[76:77], v[170:171]
	v_pk_mul_f32 v[78:79], v[78:79], v[172:173]
	v_pk_mul_f32 v[72:73], v[72:73], v[174:175]
	v_pk_mul_f32 v[74:75], v[74:75], v[176:177]
	v_pk_mul_f32 v[68:69], v[68:69], v[178:179]
	v_pk_mul_f32 v[70:71], v[70:71], v[180:181]
	v_pk_mul_f32 v[64:65], v[64:65], v[182:183]
	v_pk_mul_f32 v[66:67], v[66:67], v[184:185]
	v_cvt_pk_bf16_f32 v76, v76, v77
	v_cvt_pk_bf16_f32 v77, v78, v79
	v_cvt_pk_bf16_f32 v78, v72, v73
	v_cvt_pk_bf16_f32 v79, v74, v75
	v_cvt_pk_bf16_f32 v68, v68, v69
	v_cvt_pk_bf16_f32 v69, v70, v71
	v_cvt_pk_bf16_f32 v70, v64, v65
	v_cvt_pk_bf16_f32 v71, v66, v67
	global_store_dwordx4 v162, v[76:79], s[100:101]
	global_store_dwordx4 v162, v[68:71], s[100:101] offset:256
	s_add_u32 s100, s100, 0x14000
	s_addc_u32 s101, s101, 0
	v_pk_mul_f32 v[60:61], v[60:61], v[158:159] op_sel_hi:[1,0]
	v_pk_mul_f32 v[62:63], v[62:63], v[158:159] op_sel_hi:[1,0]
	v_pk_mul_f32 v[56:57], v[56:57], v[158:159] op_sel_hi:[1,0]
	v_pk_mul_f32 v[58:59], v[58:59], v[158:159] op_sel_hi:[1,0]
	v_pk_mul_f32 v[52:53], v[52:53], v[158:159] op_sel_hi:[1,0]
	v_pk_mul_f32 v[54:55], v[54:55], v[158:159] op_sel_hi:[1,0]
	v_pk_mul_f32 v[48:49], v[48:49], v[158:159] op_sel_hi:[1,0]
	v_pk_mul_f32 v[50:51], v[50:51], v[158:159] op_sel_hi:[1,0]
	v_pk_mul_f32 v[186:187], v[60:61], s[4:5]
	v_pk_mul_f32 v[188:189], v[62:63], s[4:5]
	v_pk_mul_f32 v[190:191], v[56:57], s[4:5]
	v_pk_mul_f32 v[192:193], v[58:59], s[4:5]
	v_pk_mul_f32 v[194:195], v[52:53], s[4:5]
	v_pk_mul_f32 v[196:197], v[54:55], s[4:5]
	v_pk_mul_f32 v[198:199], v[48:49], s[4:5]
	v_pk_mul_f32 v[200:201], v[50:51], s[4:5]
	v_exp_f32_e32 v186, v186
	v_exp_f32_e32 v187, v187
	v_exp_f32_e32 v188, v188
	v_exp_f32_e32 v189, v189
	v_exp_f32_e32 v190, v190
	v_exp_f32_e32 v191, v191
	v_exp_f32_e32 v192, v192
	v_exp_f32_e32 v193, v193
	v_exp_f32_e32 v194, v194
	v_exp_f32_e32 v195, v195
	v_exp_f32_e32 v196, v196
	v_exp_f32_e32 v197, v197
	v_exp_f32_e32 v198, v198
	v_exp_f32_e32 v199, v199
	v_exp_f32_e32 v200, v200
	v_exp_f32_e32 v201, v201
	v_add_f32_e32 v186, 1.0, v186
	v_add_f32_e32 v187, 1.0, v187
	v_add_f32_e32 v188, 1.0, v188
	v_add_f32_e32 v189, 1.0, v189
	v_add_f32_e32 v190, 1.0, v190
	v_add_f32_e32 v191, 1.0, v191
	v_add_f32_e32 v192, 1.0, v192
	v_add_f32_e32 v193, 1.0, v193
	v_add_f32_e32 v194, 1.0, v194
	v_add_f32_e32 v195, 1.0, v195
	v_add_f32_e32 v196, 1.0, v196
	v_add_f32_e32 v197, 1.0, v197
	v_add_f32_e32 v198, 1.0, v198
	v_add_f32_e32 v199, 1.0, v199
	v_add_f32_e32 v200, 1.0, v200
	v_add_f32_e32 v201, 1.0, v201
	v_rcp_f32_e32 v186, v186
	v_rcp_f32_e32 v187, v187
	v_rcp_f32_e32 v188, v188
	v_rcp_f32_e32 v189, v189
	v_rcp_f32_e32 v190, v190
	v_rcp_f32_e32 v191, v191
	v_rcp_f32_e32 v192, v192
	v_rcp_f32_e32 v193, v193
	v_rcp_f32_e32 v194, v194
	v_rcp_f32_e32 v195, v195
	v_rcp_f32_e32 v196, v196
	v_rcp_f32_e32 v197, v197
	v_rcp_f32_e32 v198, v198
	v_rcp_f32_e32 v199, v199
	v_rcp_f32_e32 v200, v200
	v_rcp_f32_e32 v201, v201
	v_pk_mul_f32 v[60:61], v[60:61], v[186:187]
	v_pk_mul_f32 v[62:63], v[62:63], v[188:189]
	v_pk_mul_f32 v[56:57], v[56:57], v[190:191]
	v_pk_mul_f32 v[58:59], v[58:59], v[192:193]
	v_pk_mul_f32 v[52:53], v[52:53], v[194:195]
	v_pk_mul_f32 v[54:55], v[54:55], v[196:197]
	v_pk_mul_f32 v[48:49], v[48:49], v[198:199]
	v_pk_mul_f32 v[50:51], v[50:51], v[200:201]
	v_pk_mul_f32 v[60:61], v[60:61], v[170:171]
	v_pk_mul_f32 v[62:63], v[62:63], v[172:173]
	v_pk_mul_f32 v[56:57], v[56:57], v[174:175]
	v_pk_mul_f32 v[58:59], v[58:59], v[176:177]
	v_pk_mul_f32 v[52:53], v[52:53], v[178:179]
	v_pk_mul_f32 v[54:55], v[54:55], v[180:181]
	v_pk_mul_f32 v[48:49], v[48:49], v[182:183]
	v_pk_mul_f32 v[50:51], v[50:51], v[184:185]
	v_cvt_pk_bf16_f32 v60, v60, v61
	v_cvt_pk_bf16_f32 v61, v62, v63
	v_cvt_pk_bf16_f32 v62, v56, v57
	v_cvt_pk_bf16_f32 v63, v58, v59
	v_cvt_pk_bf16_f32 v52, v52, v53
	v_cvt_pk_bf16_f32 v53, v54, v55
	v_cvt_pk_bf16_f32 v54, v48, v49
	v_cvt_pk_bf16_f32 v55, v50, v51
	global_store_dwordx4 v162, v[60:63], s[100:101]
	global_store_dwordx4 v162, v[52:55], s[100:101] offset:256
	s_add_u32 s100, s100, 0x4000
	s_addc_u32 s101, s101, 0
	v_pk_mul_f32 v[44:45], v[44:45], v[158:159] op_sel:[0,1] op_sel_hi:[1,1]
	v_pk_mul_f32 v[46:47], v[46:47], v[158:159] op_sel:[0,1] op_sel_hi:[1,1]
	v_pk_mul_f32 v[40:41], v[40:41], v[158:159] op_sel:[0,1] op_sel_hi:[1,1]
	v_pk_mul_f32 v[42:43], v[42:43], v[158:159] op_sel:[0,1] op_sel_hi:[1,1]
	v_pk_mul_f32 v[36:37], v[36:37], v[158:159] op_sel:[0,1] op_sel_hi:[1,1]
	v_pk_mul_f32 v[38:39], v[38:39], v[158:159] op_sel:[0,1] op_sel_hi:[1,1]
	v_pk_mul_f32 v[32:33], v[32:33], v[158:159] op_sel:[0,1] op_sel_hi:[1,1]
	v_pk_mul_f32 v[34:35], v[34:35], v[158:159] op_sel:[0,1] op_sel_hi:[1,1]
	v_pk_mul_f32 v[186:187], v[44:45], s[4:5]
	v_pk_mul_f32 v[188:189], v[46:47], s[4:5]
	v_pk_mul_f32 v[190:191], v[40:41], s[4:5]
	v_pk_mul_f32 v[192:193], v[42:43], s[4:5]
	v_pk_mul_f32 v[194:195], v[36:37], s[4:5]
	v_pk_mul_f32 v[196:197], v[38:39], s[4:5]
	v_pk_mul_f32 v[198:199], v[32:33], s[4:5]
	v_pk_mul_f32 v[200:201], v[34:35], s[4:5]
	v_exp_f32_e32 v186, v186
	v_exp_f32_e32 v187, v187
	v_exp_f32_e32 v188, v188
	v_exp_f32_e32 v189, v189
	v_exp_f32_e32 v190, v190
	v_exp_f32_e32 v191, v191
	v_exp_f32_e32 v192, v192
	v_exp_f32_e32 v193, v193
	v_exp_f32_e32 v194, v194
	v_exp_f32_e32 v195, v195
	v_exp_f32_e32 v196, v196
	v_exp_f32_e32 v197, v197
	v_exp_f32_e32 v198, v198
	v_exp_f32_e32 v199, v199
	v_exp_f32_e32 v200, v200
	v_exp_f32_e32 v201, v201
	v_add_f32_e32 v186, 1.0, v186
	v_add_f32_e32 v187, 1.0, v187
	v_add_f32_e32 v188, 1.0, v188
	v_add_f32_e32 v189, 1.0, v189
	v_add_f32_e32 v190, 1.0, v190
	v_add_f32_e32 v191, 1.0, v191
	v_add_f32_e32 v192, 1.0, v192
	v_add_f32_e32 v193, 1.0, v193
	v_add_f32_e32 v194, 1.0, v194
	v_add_f32_e32 v195, 1.0, v195
	v_add_f32_e32 v196, 1.0, v196
	v_add_f32_e32 v197, 1.0, v197
	v_add_f32_e32 v198, 1.0, v198
	v_add_f32_e32 v199, 1.0, v199
	v_add_f32_e32 v200, 1.0, v200
	v_add_f32_e32 v201, 1.0, v201
	v_rcp_f32_e32 v186, v186
	v_rcp_f32_e32 v187, v187
	v_rcp_f32_e32 v188, v188
	v_rcp_f32_e32 v189, v189
	v_rcp_f32_e32 v190, v190
	v_rcp_f32_e32 v191, v191
	v_rcp_f32_e32 v192, v192
	v_rcp_f32_e32 v193, v193
	v_rcp_f32_e32 v194, v194
	v_rcp_f32_e32 v195, v195
	v_rcp_f32_e32 v196, v196
	v_rcp_f32_e32 v197, v197
	v_rcp_f32_e32 v198, v198
	v_rcp_f32_e32 v199, v199
	v_rcp_f32_e32 v200, v200
	v_rcp_f32_e32 v201, v201
	v_pk_mul_f32 v[44:45], v[44:45], v[186:187]
	v_pk_mul_f32 v[46:47], v[46:47], v[188:189]
	v_pk_mul_f32 v[40:41], v[40:41], v[190:191]
	v_pk_mul_f32 v[42:43], v[42:43], v[192:193]
	v_pk_mul_f32 v[36:37], v[36:37], v[194:195]
	v_pk_mul_f32 v[38:39], v[38:39], v[196:197]
	v_pk_mul_f32 v[32:33], v[32:33], v[198:199]
	v_pk_mul_f32 v[34:35], v[34:35], v[200:201]
	v_pk_mul_f32 v[44:45], v[44:45], v[170:171]
	v_pk_mul_f32 v[46:47], v[46:47], v[172:173]
	v_pk_mul_f32 v[40:41], v[40:41], v[174:175]
	v_pk_mul_f32 v[42:43], v[42:43], v[176:177]
	v_pk_mul_f32 v[36:37], v[36:37], v[178:179]
	v_pk_mul_f32 v[38:39], v[38:39], v[180:181]
	v_pk_mul_f32 v[32:33], v[32:33], v[182:183]
	v_pk_mul_f32 v[34:35], v[34:35], v[184:185]
	v_cvt_pk_bf16_f32 v44, v44, v45
	v_cvt_pk_bf16_f32 v45, v46, v47
	v_cvt_pk_bf16_f32 v46, v40, v41
	v_cvt_pk_bf16_f32 v47, v42, v43
	v_cvt_pk_bf16_f32 v36, v36, v37
	v_cvt_pk_bf16_f32 v37, v38, v39
	v_cvt_pk_bf16_f32 v38, v32, v33
	v_cvt_pk_bf16_f32 v39, v34, v35
	global_store_dwordx4 v162, v[44:47], s[100:101]
	global_store_dwordx4 v162, v[36:39], s[100:101] offset:256
	s_add_u32 s100, s100, 0x4000
	s_addc_u32 s101, s101, 0
	v_pk_mul_f32 v[28:29], v[28:29], v[160:161] op_sel_hi:[1,0]
	v_pk_mul_f32 v[30:31], v[30:31], v[160:161] op_sel_hi:[1,0]
	v_pk_mul_f32 v[24:25], v[24:25], v[160:161] op_sel_hi:[1,0]
	v_pk_mul_f32 v[26:27], v[26:27], v[160:161] op_sel_hi:[1,0]
	v_pk_mul_f32 v[20:21], v[20:21], v[160:161] op_sel_hi:[1,0]
	v_pk_mul_f32 v[22:23], v[22:23], v[160:161] op_sel_hi:[1,0]
	v_pk_mul_f32 v[16:17], v[16:17], v[160:161] op_sel_hi:[1,0]
	v_pk_mul_f32 v[18:19], v[18:19], v[160:161] op_sel_hi:[1,0]
	v_pk_mul_f32 v[186:187], v[28:29], s[4:5]
	v_pk_mul_f32 v[188:189], v[30:31], s[4:5]
	v_pk_mul_f32 v[190:191], v[24:25], s[4:5]
	v_pk_mul_f32 v[192:193], v[26:27], s[4:5]
	v_pk_mul_f32 v[194:195], v[20:21], s[4:5]
	v_pk_mul_f32 v[196:197], v[22:23], s[4:5]
	v_pk_mul_f32 v[198:199], v[16:17], s[4:5]
	v_pk_mul_f32 v[200:201], v[18:19], s[4:5]
	v_exp_f32_e32 v186, v186
	v_exp_f32_e32 v187, v187
	v_exp_f32_e32 v188, v188
	v_exp_f32_e32 v189, v189
	v_exp_f32_e32 v190, v190
	v_exp_f32_e32 v191, v191
	v_exp_f32_e32 v192, v192
	v_exp_f32_e32 v193, v193
	v_exp_f32_e32 v194, v194
	v_exp_f32_e32 v195, v195
	v_exp_f32_e32 v196, v196
	v_exp_f32_e32 v197, v197
	v_exp_f32_e32 v198, v198
	v_exp_f32_e32 v199, v199
	v_exp_f32_e32 v200, v200
	v_exp_f32_e32 v201, v201
	v_add_f32_e32 v186, 1.0, v186
	v_add_f32_e32 v187, 1.0, v187
	v_add_f32_e32 v188, 1.0, v188
	v_add_f32_e32 v189, 1.0, v189
	v_add_f32_e32 v190, 1.0, v190
	v_add_f32_e32 v191, 1.0, v191
	v_add_f32_e32 v192, 1.0, v192
	v_add_f32_e32 v193, 1.0, v193
	v_add_f32_e32 v194, 1.0, v194
	v_add_f32_e32 v195, 1.0, v195
	v_add_f32_e32 v196, 1.0, v196
	v_add_f32_e32 v197, 1.0, v197
	v_add_f32_e32 v198, 1.0, v198
	v_add_f32_e32 v199, 1.0, v199
	v_add_f32_e32 v200, 1.0, v200
	v_add_f32_e32 v201, 1.0, v201
	v_rcp_f32_e32 v186, v186
	v_rcp_f32_e32 v187, v187
	v_rcp_f32_e32 v188, v188
	v_rcp_f32_e32 v189, v189
	v_rcp_f32_e32 v190, v190
	v_rcp_f32_e32 v191, v191
	v_rcp_f32_e32 v192, v192
	v_rcp_f32_e32 v193, v193
	v_rcp_f32_e32 v194, v194
	v_rcp_f32_e32 v195, v195
	v_rcp_f32_e32 v196, v196
	v_rcp_f32_e32 v197, v197
	v_rcp_f32_e32 v198, v198
	v_rcp_f32_e32 v199, v199
	v_rcp_f32_e32 v200, v200
	v_rcp_f32_e32 v201, v201
	v_pk_mul_f32 v[28:29], v[28:29], v[186:187]
	v_pk_mul_f32 v[30:31], v[30:31], v[188:189]
	v_pk_mul_f32 v[24:25], v[24:25], v[190:191]
	v_pk_mul_f32 v[26:27], v[26:27], v[192:193]
	v_pk_mul_f32 v[20:21], v[20:21], v[194:195]
	v_pk_mul_f32 v[22:23], v[22:23], v[196:197]
	v_pk_mul_f32 v[16:17], v[16:17], v[198:199]
	v_pk_mul_f32 v[18:19], v[18:19], v[200:201]
	v_pk_mul_f32 v[28:29], v[28:29], v[170:171]
	v_pk_mul_f32 v[30:31], v[30:31], v[172:173]
	v_pk_mul_f32 v[24:25], v[24:25], v[174:175]
	v_pk_mul_f32 v[26:27], v[26:27], v[176:177]
	v_pk_mul_f32 v[20:21], v[20:21], v[178:179]
	v_pk_mul_f32 v[22:23], v[22:23], v[180:181]
	v_pk_mul_f32 v[16:17], v[16:17], v[182:183]
	v_pk_mul_f32 v[18:19], v[18:19], v[184:185]
	v_cvt_pk_bf16_f32 v28, v28, v29
	v_cvt_pk_bf16_f32 v29, v30, v31
	v_cvt_pk_bf16_f32 v30, v24, v25
	v_cvt_pk_bf16_f32 v31, v26, v27
	v_cvt_pk_bf16_f32 v20, v20, v21
	v_cvt_pk_bf16_f32 v21, v22, v23
	v_cvt_pk_bf16_f32 v22, v16, v17
	v_cvt_pk_bf16_f32 v23, v18, v19
	global_store_dwordx4 v162, v[28:31], s[100:101]
	global_store_dwordx4 v162, v[20:23], s[100:101] offset:256
	s_add_u32 s100, s100, 0x4000
	s_addc_u32 s101, s101, 0
	v_pk_mul_f32 v[12:13], v[12:13], v[160:161] op_sel:[0,1] op_sel_hi:[1,1]
	v_pk_mul_f32 v[14:15], v[14:15], v[160:161] op_sel:[0,1] op_sel_hi:[1,1]
	v_pk_mul_f32 v[8:9], v[8:9], v[160:161] op_sel:[0,1] op_sel_hi:[1,1]
	v_pk_mul_f32 v[10:11], v[10:11], v[160:161] op_sel:[0,1] op_sel_hi:[1,1]
	v_pk_mul_f32 v[4:5], v[4:5], v[160:161] op_sel:[0,1] op_sel_hi:[1,1]
	v_pk_mul_f32 v[6:7], v[6:7], v[160:161] op_sel:[0,1] op_sel_hi:[1,1]
	v_pk_mul_f32 v[0:1], v[0:1], v[160:161] op_sel:[0,1] op_sel_hi:[1,1]
	v_pk_mul_f32 v[2:3], v[2:3], v[160:161] op_sel:[0,1] op_sel_hi:[1,1]
	v_pk_mul_f32 v[186:187], v[12:13], s[4:5]
	v_pk_mul_f32 v[188:189], v[14:15], s[4:5]
	v_pk_mul_f32 v[190:191], v[8:9], s[4:5]
	v_pk_mul_f32 v[192:193], v[10:11], s[4:5]
	v_pk_mul_f32 v[194:195], v[4:5], s[4:5]
	v_pk_mul_f32 v[196:197], v[6:7], s[4:5]
	v_pk_mul_f32 v[198:199], v[0:1], s[4:5]
	v_pk_mul_f32 v[200:201], v[2:3], s[4:5]
	v_exp_f32_e32 v186, v186
	v_exp_f32_e32 v187, v187
	v_exp_f32_e32 v188, v188
	v_exp_f32_e32 v189, v189
	v_exp_f32_e32 v190, v190
	v_exp_f32_e32 v191, v191
	v_exp_f32_e32 v192, v192
	v_exp_f32_e32 v193, v193
	v_exp_f32_e32 v194, v194
	v_exp_f32_e32 v195, v195
	v_exp_f32_e32 v196, v196
	v_exp_f32_e32 v197, v197
	v_exp_f32_e32 v198, v198
	v_exp_f32_e32 v199, v199
	v_exp_f32_e32 v200, v200
	v_exp_f32_e32 v201, v201
	v_add_f32_e32 v186, 1.0, v186
	v_add_f32_e32 v187, 1.0, v187
	v_add_f32_e32 v188, 1.0, v188
	v_add_f32_e32 v189, 1.0, v189
	v_add_f32_e32 v190, 1.0, v190
	v_add_f32_e32 v191, 1.0, v191
	v_add_f32_e32 v192, 1.0, v192
	v_add_f32_e32 v193, 1.0, v193
	v_add_f32_e32 v194, 1.0, v194
	v_add_f32_e32 v195, 1.0, v195
	v_add_f32_e32 v196, 1.0, v196
	v_add_f32_e32 v197, 1.0, v197
	v_add_f32_e32 v198, 1.0, v198
	v_add_f32_e32 v199, 1.0, v199
	v_add_f32_e32 v200, 1.0, v200
	v_add_f32_e32 v201, 1.0, v201
	v_rcp_f32_e32 v186, v186
	v_rcp_f32_e32 v187, v187
	v_rcp_f32_e32 v188, v188
	v_rcp_f32_e32 v189, v189
	v_rcp_f32_e32 v190, v190
	v_rcp_f32_e32 v191, v191
	v_rcp_f32_e32 v192, v192
	v_rcp_f32_e32 v193, v193
	v_rcp_f32_e32 v194, v194
	v_rcp_f32_e32 v195, v195
	v_rcp_f32_e32 v196, v196
	v_rcp_f32_e32 v197, v197
	v_rcp_f32_e32 v198, v198
	v_rcp_f32_e32 v199, v199
	v_rcp_f32_e32 v200, v200
	v_rcp_f32_e32 v201, v201
	v_pk_mul_f32 v[12:13], v[12:13], v[186:187]
	v_pk_mul_f32 v[14:15], v[14:15], v[188:189]
	v_pk_mul_f32 v[8:9], v[8:9], v[190:191]
	v_pk_mul_f32 v[10:11], v[10:11], v[192:193]
	v_pk_mul_f32 v[4:5], v[4:5], v[194:195]
	v_pk_mul_f32 v[6:7], v[6:7], v[196:197]
	v_pk_mul_f32 v[0:1], v[0:1], v[198:199]
	v_pk_mul_f32 v[2:3], v[2:3], v[200:201]
	v_pk_mul_f32 v[12:13], v[12:13], v[170:171]
	v_pk_mul_f32 v[14:15], v[14:15], v[172:173]
	v_pk_mul_f32 v[8:9], v[8:9], v[174:175]
	v_pk_mul_f32 v[10:11], v[10:11], v[176:177]
	v_pk_mul_f32 v[4:5], v[4:5], v[178:179]
	v_pk_mul_f32 v[6:7], v[6:7], v[180:181]
	v_pk_mul_f32 v[0:1], v[0:1], v[182:183]
	v_pk_mul_f32 v[2:3], v[2:3], v[184:185]
	v_cvt_pk_bf16_f32 v12, v12, v13
	v_cvt_pk_bf16_f32 v13, v14, v15
	v_cvt_pk_bf16_f32 v14, v8, v9
	v_cvt_pk_bf16_f32 v15, v10, v11
	v_cvt_pk_bf16_f32 v4, v4, v5
	v_cvt_pk_bf16_f32 v5, v6, v7
	v_cvt_pk_bf16_f32 v6, v0, v1
	v_cvt_pk_bf16_f32 v7, v2, v3
	global_store_dwordx4 v162, v[12:15], s[100:101]
	global_store_dwordx4 v162, v[4:7], s[100:101] offset:256
	s_branch .Lei_done
.Lei_glu:
	v_lshl_add_u32 v163, v150, 5, 0
	v_lshl_add_u32 v163, v149, 3, v163
	v_lshl_add_u32 v162, v163, 1, v162
	s_lshl_b32 s10, s30, 8
	s_add_i32 s10, s10, s6
	s_add_u32 s100, s88, s10
	s_addc_u32 s101, s89, 0
	v_pk_mul_f32 v[124:125], v[124:125], v[154:155] op_sel_hi:[1,0]
	v_pk_mul_f32 v[126:127], v[126:127], v[154:155] op_sel_hi:[1,0]
	v_pk_mul_f32 v[120:121], v[120:121], v[154:155] op_sel_hi:[1,0]
	v_pk_mul_f32 v[122:123], v[122:123], v[154:155] op_sel_hi:[1,0]
	v_pk_mul_f32 v[116:117], v[116:117], v[154:155] op_sel_hi:[1,0]
	v_pk_mul_f32 v[118:119], v[118:119], v[154:155] op_sel_hi:[1,0]
	v_pk_mul_f32 v[112:113], v[112:113], v[154:155] op_sel_hi:[1,0]
	v_pk_mul_f32 v[114:115], v[114:115], v[154:155] op_sel_hi:[1,0]
	v_pk_mul_f32 v[186:187], v[116:117], s[4:5]
	v_pk_mul_f32 v[188:189], v[118:119], s[4:5]
	v_pk_mul_f32 v[190:191], v[112:113], s[4:5]
	v_pk_mul_f32 v[192:193], v[114:115], s[4:5]
	v_exp_f32_e32 v186, v186
	v_exp_f32_e32 v187, v187
	v_exp_f32_e32 v188, v188
	v_exp_f32_e32 v189, v189
	v_exp_f32_e32 v190, v190
	v_exp_f32_e32 v191, v191
	v_exp_f32_e32 v192, v192
	v_exp_f32_e32 v193, v193
	v_add_f32_e32 v186, 1.0, v186
	v_add_f32_e32 v187, 1.0, v187
	v_add_f32_e32 v188, 1.0, v188
	v_add_f32_e32 v189, 1.0, v189
	v_add_f32_e32 v190, 1.0, v190
	v_add_f32_e32 v191, 1.0, v191
	v_add_f32_e32 v192, 1.0, v192
	v_add_f32_e32 v193, 1.0, v193
	v_rcp_f32_e32 v186, v186
	v_rcp_f32_e32 v187, v187
	v_rcp_f32_e32 v188, v188
	v_rcp_f32_e32 v189, v189
	v_rcp_f32_e32 v190, v190
	v_rcp_f32_e32 v191, v191
	v_rcp_f32_e32 v192, v192
	v_rcp_f32_e32 v193, v193
	v_pk_mul_f32 v[124:125], v[124:125], v[186:187]
	v_pk_mul_f32 v[126:127], v[126:127], v[188:189]
	v_pk_mul_f32 v[120:121], v[120:121], v[190:191]
	v_pk_mul_f32 v[122:123], v[122:123], v[192:193]
	v_cvt_pk_bf16_f32 v124, v124, v125
	v_cvt_pk_bf16_f32 v125, v126, v127
	v_cvt_pk_bf16_f32 v126, v120, v121
	v_cvt_pk_bf16_f32 v127, v122, v123
	global_store_dwordx4 v162, v[124:127], s[100:101]
	s_add_u32 s100, s100, 0x4000
	s_addc_u32 s101, s101, 0
	v_pk_mul_f32 v[108:109], v[108:109], v[154:155] op_sel:[0,1] op_sel_hi:[1,1]
	v_pk_mul_f32 v[110:111], v[110:111], v[154:155] op_sel:[0,1] op_sel_hi:[1,1]
	v_pk_mul_f32 v[104:105], v[104:105], v[154:155] op_sel:[0,1] op_sel_hi:[1,1]
	v_pk_mul_f32 v[106:107], v[106:107], v[154:155] op_sel:[0,1] op_sel_hi:[1,1]
	v_pk_mul_f32 v[100:101], v[100:101], v[154:155] op_sel:[0,1] op_sel_hi:[1,1]
	v_pk_mul_f32 v[102:103], v[102:103], v[154:155] op_sel:[0,1] op_sel_hi:[1,1]
	v_pk_mul_f32 v[96:97], v[96:97], v[154:155] op_sel:[0,1] op_sel_hi:[1,1]
	v_pk_mul_f32 v[98:99], v[98:99], v[154:155] op_sel:[0,1] op_sel_hi:[1,1]
	v_pk_mul_f32 v[186:187], v[100:101], s[4:5]
	v_pk_mul_f32 v[188:189], v[102:103], s[4:5]
	v_pk_mul_f32 v[190:191], v[96:97], s[4:5]
	v_pk_mul_f32 v[192:193], v[98:99], s[4:5]
	v_exp_f32_e32 v186, v186
	v_exp_f32_e32 v187, v187
	v_exp_f32_e32 v188, v188
	v_exp_f32_e32 v189, v189
	v_exp_f32_e32 v190, v190
	v_exp_f32_e32 v191, v191
	v_exp_f32_e32 v192, v192
	v_exp_f32_e32 v193, v193
	v_add_f32_e32 v186, 1.0, v186
	v_add_f32_e32 v187, 1.0, v187
	v_add_f32_e32 v188, 1.0, v188
	v_add_f32_e32 v189, 1.0, v189
	v_add_f32_e32 v190, 1.0, v190
	v_add_f32_e32 v191, 1.0, v191
	v_add_f32_e32 v192, 1.0, v192
	v_add_f32_e32 v193, 1.0, v193
	v_rcp_f32_e32 v186, v186
	v_rcp_f32_e32 v187, v187
	v_rcp_f32_e32 v188, v188
	v_rcp_f32_e32 v189, v189
	v_rcp_f32_e32 v190, v190
	v_rcp_f32_e32 v191, v191
	v_rcp_f32_e32 v192, v192
	v_rcp_f32_e32 v193, v193
	v_pk_mul_f32 v[108:109], v[108:109], v[186:187]
	v_pk_mul_f32 v[110:111], v[110:111], v[188:189]
	v_pk_mul_f32 v[104:105], v[104:105], v[190:191]
	v_pk_mul_f32 v[106:107], v[106:107], v[192:193]
	v_cvt_pk_bf16_f32 v108, v108, v109
	v_cvt_pk_bf16_f32 v109, v110, v111
	v_cvt_pk_bf16_f32 v110, v104, v105
	v_cvt_pk_bf16_f32 v111, v106, v107
	global_store_dwordx4 v162, v[108:111], s[100:101]
	s_add_u32 s100, s100, 0x4000
	s_addc_u32 s101, s101, 0
	v_pk_mul_f32 v[92:93], v[92:93], v[156:157] op_sel_hi:[1,0]
	v_pk_mul_f32 v[94:95], v[94:95], v[156:157] op_sel_hi:[1,0]
	v_pk_mul_f32 v[88:89], v[88:89], v[156:157] op_sel_hi:[1,0]
	v_pk_mul_f32 v[90:91], v[90:91], v[156:157] op_sel_hi:[1,0]
	v_pk_mul_f32 v[84:85], v[84:85], v[156:157] op_sel_hi:[1,0]
	v_pk_mul_f32 v[86:87], v[86:87], v[156:157] op_sel_hi:[1,0]
	v_pk_mul_f32 v[80:81], v[80:81], v[156:157] op_sel_hi:[1,0]
	v_pk_mul_f32 v[82:83], v[82:83], v[156:157] op_sel_hi:[1,0]
	v_pk_mul_f32 v[186:187], v[84:85], s[4:5]
	v_pk_mul_f32 v[188:189], v[86:87], s[4:5]
	v_pk_mul_f32 v[190:191], v[80:81], s[4:5]
	v_pk_mul_f32 v[192:193], v[82:83], s[4:5]
	v_exp_f32_e32 v186, v186
	v_exp_f32_e32 v187, v187
	v_exp_f32_e32 v188, v188
	v_exp_f32_e32 v189, v189
	v_exp_f32_e32 v190, v190
	v_exp_f32_e32 v191, v191
	v_exp_f32_e32 v192, v192
	v_exp_f32_e32 v193, v193
	v_add_f32_e32 v186, 1.0, v186
	v_add_f32_e32 v187, 1.0, v187
	v_add_f32_e32 v188, 1.0, v188
	v_add_f32_e32 v189, 1.0, v189
	v_add_f32_e32 v190, 1.0, v190
	v_add_f32_e32 v191, 1.0, v191
	v_add_f32_e32 v192, 1.0, v192
	v_add_f32_e32 v193, 1.0, v193
	v_rcp_f32_e32 v186, v186
	v_rcp_f32_e32 v187, v187
	v_rcp_f32_e32 v188, v188
	v_rcp_f32_e32 v189, v189
	v_rcp_f32_e32 v190, v190
	v_rcp_f32_e32 v191, v191
	v_rcp_f32_e32 v192, v192
	v_rcp_f32_e32 v193, v193
	v_pk_mul_f32 v[92:93], v[92:93], v[186:187]
	v_pk_mul_f32 v[94:95], v[94:95], v[188:189]
	v_pk_mul_f32 v[88:89], v[88:89], v[190:191]
	v_pk_mul_f32 v[90:91], v[90:91], v[192:193]
	v_cvt_pk_bf16_f32 v92, v92, v93
	v_cvt_pk_bf16_f32 v93, v94, v95
	v_cvt_pk_bf16_f32 v94, v88, v89
	v_cvt_pk_bf16_f32 v95, v90, v91
	global_store_dwordx4 v162, v[92:95], s[100:101]
	s_add_u32 s100, s100, 0x4000
	s_addc_u32 s101, s101, 0
	v_pk_mul_f32 v[76:77], v[76:77], v[156:157] op_sel:[0,1] op_sel_hi:[1,1]
	v_pk_mul_f32 v[78:79], v[78:79], v[156:157] op_sel:[0,1] op_sel_hi:[1,1]
	v_pk_mul_f32 v[72:73], v[72:73], v[156:157] op_sel:[0,1] op_sel_hi:[1,1]
	v_pk_mul_f32 v[74:75], v[74:75], v[156:157] op_sel:[0,1] op_sel_hi:[1,1]
	v_pk_mul_f32 v[68:69], v[68:69], v[156:157] op_sel:[0,1] op_sel_hi:[1,1]
	v_pk_mul_f32 v[70:71], v[70:71], v[156:157] op_sel:[0,1] op_sel_hi:[1,1]
	v_pk_mul_f32 v[64:65], v[64:65], v[156:157] op_sel:[0,1] op_sel_hi:[1,1]
	v_pk_mul_f32 v[66:67], v[66:67], v[156:157] op_sel:[0,1] op_sel_hi:[1,1]
	v_pk_mul_f32 v[186:187], v[68:69], s[4:5]
	v_pk_mul_f32 v[188:189], v[70:71], s[4:5]
	v_pk_mul_f32 v[190:191], v[64:65], s[4:5]
	v_pk_mul_f32 v[192:193], v[66:67], s[4:5]
	v_exp_f32_e32 v186, v186
	v_exp_f32_e32 v187, v187
	v_exp_f32_e32 v188, v188
	v_exp_f32_e32 v189, v189
	v_exp_f32_e32 v190, v190
	v_exp_f32_e32 v191, v191
	v_exp_f32_e32 v192, v192
	v_exp_f32_e32 v193, v193
	v_add_f32_e32 v186, 1.0, v186
	v_add_f32_e32 v187, 1.0, v187
	v_add_f32_e32 v188, 1.0, v188
	v_add_f32_e32 v189, 1.0, v189
	v_add_f32_e32 v190, 1.0, v190
	v_add_f32_e32 v191, 1.0, v191
	v_add_f32_e32 v192, 1.0, v192
	v_add_f32_e32 v193, 1.0, v193
	v_rcp_f32_e32 v186, v186
	v_rcp_f32_e32 v187, v187
	v_rcp_f32_e32 v188, v188
	v_rcp_f32_e32 v189, v189
	v_rcp_f32_e32 v190, v190
	v_rcp_f32_e32 v191, v191
	v_rcp_f32_e32 v192, v192
	v_rcp_f32_e32 v193, v193
	v_pk_mul_f32 v[76:77], v[76:77], v[186:187]
	v_pk_mul_f32 v[78:79], v[78:79], v[188:189]
	v_pk_mul_f32 v[72:73], v[72:73], v[190:191]
	v_pk_mul_f32 v[74:75], v[74:75], v[192:193]
	v_cvt_pk_bf16_f32 v76, v76, v77
	v_cvt_pk_bf16_f32 v77, v78, v79
	v_cvt_pk_bf16_f32 v78, v72, v73
	v_cvt_pk_bf16_f32 v79, v74, v75
	global_store_dwordx4 v162, v[76:79], s[100:101]
	s_add_u32 s100, s100, 0x14000
	s_addc_u32 s101, s101, 0
	v_pk_mul_f32 v[60:61], v[60:61], v[158:159] op_sel_hi:[1,0]
	v_pk_mul_f32 v[62:63], v[62:63], v[158:159] op_sel_hi:[1,0]
	v_pk_mul_f32 v[56:57], v[56:57], v[158:159] op_sel_hi:[1,0]
	v_pk_mul_f32 v[58:59], v[58:59], v[158:159] op_sel_hi:[1,0]
	v_pk_mul_f32 v[52:53], v[52:53], v[158:159] op_sel_hi:[1,0]
	v_pk_mul_f32 v[54:55], v[54:55], v[158:159] op_sel_hi:[1,0]
	v_pk_mul_f32 v[48:49], v[48:49], v[158:159] op_sel_hi:[1,0]
	v_pk_mul_f32 v[50:51], v[50:51], v[158:159] op_sel_hi:[1,0]
	v_pk_mul_f32 v[186:187], v[52:53], s[4:5]
	v_pk_mul_f32 v[188:189], v[54:55], s[4:5]
	v_pk_mul_f32 v[190:191], v[48:49], s[4:5]
	v_pk_mul_f32 v[192:193], v[50:51], s[4:5]
	v_exp_f32_e32 v186, v186
	v_exp_f32_e32 v187, v187
	v_exp_f32_e32 v188, v188
	v_exp_f32_e32 v189, v189
	v_exp_f32_e32 v190, v190
	v_exp_f32_e32 v191, v191
	v_exp_f32_e32 v192, v192
	v_exp_f32_e32 v193, v193
	v_add_f32_e32 v186, 1.0, v186
	v_add_f32_e32 v187, 1.0, v187
	v_add_f32_e32 v188, 1.0, v188
	v_add_f32_e32 v189, 1.0, v189
	v_add_f32_e32 v190, 1.0, v190
	v_add_f32_e32 v191, 1.0, v191
	v_add_f32_e32 v192, 1.0, v192
	v_add_f32_e32 v193, 1.0, v193
	v_rcp_f32_e32 v186, v186
	v_rcp_f32_e32 v187, v187
	v_rcp_f32_e32 v188, v188
	v_rcp_f32_e32 v189, v189
	v_rcp_f32_e32 v190, v190
	v_rcp_f32_e32 v191, v191
	v_rcp_f32_e32 v192, v192
	v_rcp_f32_e32 v193, v193
	v_pk_mul_f32 v[60:61], v[60:61], v[186:187]
	v_pk_mul_f32 v[62:63], v[62:63], v[188:189]
	v_pk_mul_f32 v[56:57], v[56:57], v[190:191]
	v_pk_mul_f32 v[58:59], v[58:59], v[192:193]
	v_cvt_pk_bf16_f32 v60, v60, v61
	v_cvt_pk_bf16_f32 v61, v62, v63
	v_cvt_pk_bf16_f32 v62, v56, v57
	v_cvt_pk_bf16_f32 v63, v58, v59
	global_store_dwordx4 v162, v[60:63], s[100:101]
	s_add_u32 s100, s100, 0x4000
	s_addc_u32 s101, s101, 0
	v_pk_mul_f32 v[44:45], v[44:45], v[158:159] op_sel:[0,1] op_sel_hi:[1,1]
	v_pk_mul_f32 v[46:47], v[46:47], v[158:159] op_sel:[0,1] op_sel_hi:[1,1]
	v_pk_mul_f32 v[40:41], v[40:41], v[158:159] op_sel:[0,1] op_sel_hi:[1,1]
	v_pk_mul_f32 v[42:43], v[42:43], v[158:159] op_sel:[0,1] op_sel_hi:[1,1]
	v_pk_mul_f32 v[36:37], v[36:37], v[158:159] op_sel:[0,1] op_sel_hi:[1,1]
	v_pk_mul_f32 v[38:39], v[38:39], v[158:159] op_sel:[0,1] op_sel_hi:[1,1]
	v_pk_mul_f32 v[32:33], v[32:33], v[158:159] op_sel:[0,1] op_sel_hi:[1,1]
	v_pk_mul_f32 v[34:35], v[34:35], v[158:159] op_sel:[0,1] op_sel_hi:[1,1]
	v_pk_mul_f32 v[186:187], v[36:37], s[4:5]
	v_pk_mul_f32 v[188:189], v[38:39], s[4:5]
	v_pk_mul_f32 v[190:191], v[32:33], s[4:5]
	v_pk_mul_f32 v[192:193], v[34:35], s[4:5]
	v_exp_f32_e32 v186, v186
	v_exp_f32_e32 v187, v187
	v_exp_f32_e32 v188, v188
	v_exp_f32_e32 v189, v189
	v_exp_f32_e32 v190, v190
	v_exp_f32_e32 v191, v191
	v_exp_f32_e32 v192, v192
	v_exp_f32_e32 v193, v193
	v_add_f32_e32 v186, 1.0, v186
	v_add_f32_e32 v187, 1.0, v187
	v_add_f32_e32 v188, 1.0, v188
	v_add_f32_e32 v189, 1.0, v189
	v_add_f32_e32 v190, 1.0, v190
	v_add_f32_e32 v191, 1.0, v191
	v_add_f32_e32 v192, 1.0, v192
	v_add_f32_e32 v193, 1.0, v193
	v_rcp_f32_e32 v186, v186
	v_rcp_f32_e32 v187, v187
	v_rcp_f32_e32 v188, v188
	v_rcp_f32_e32 v189, v189
	v_rcp_f32_e32 v190, v190
	v_rcp_f32_e32 v191, v191
	v_rcp_f32_e32 v192, v192
	v_rcp_f32_e32 v193, v193
	v_pk_mul_f32 v[44:45], v[44:45], v[186:187]
	v_pk_mul_f32 v[46:47], v[46:47], v[188:189]
	v_pk_mul_f32 v[40:41], v[40:41], v[190:191]
	v_pk_mul_f32 v[42:43], v[42:43], v[192:193]
	v_cvt_pk_bf16_f32 v44, v44, v45
	v_cvt_pk_bf16_f32 v45, v46, v47
	v_cvt_pk_bf16_f32 v46, v40, v41
	v_cvt_pk_bf16_f32 v47, v42, v43
	global_store_dwordx4 v162, v[44:47], s[100:101]
	s_add_u32 s100, s100, 0x4000
	s_addc_u32 s101, s101, 0
	v_pk_mul_f32 v[28:29], v[28:29], v[160:161] op_sel_hi:[1,0]
	v_pk_mul_f32 v[30:31], v[30:31], v[160:161] op_sel_hi:[1,0]
	v_pk_mul_f32 v[24:25], v[24:25], v[160:161] op_sel_hi:[1,0]
	v_pk_mul_f32 v[26:27], v[26:27], v[160:161] op_sel_hi:[1,0]
	v_pk_mul_f32 v[20:21], v[20:21], v[160:161] op_sel_hi:[1,0]
	v_pk_mul_f32 v[22:23], v[22:23], v[160:161] op_sel_hi:[1,0]
	v_pk_mul_f32 v[16:17], v[16:17], v[160:161] op_sel_hi:[1,0]
	v_pk_mul_f32 v[18:19], v[18:19], v[160:161] op_sel_hi:[1,0]
	v_pk_mul_f32 v[186:187], v[20:21], s[4:5]
	v_pk_mul_f32 v[188:189], v[22:23], s[4:5]
	v_pk_mul_f32 v[190:191], v[16:17], s[4:5]
	v_pk_mul_f32 v[192:193], v[18:19], s[4:5]
	v_exp_f32_e32 v186, v186
	v_exp_f32_e32 v187, v187
	v_exp_f32_e32 v188, v188
	v_exp_f32_e32 v189, v189
	v_exp_f32_e32 v190, v190
	v_exp_f32_e32 v191, v191
	v_exp_f32_e32 v192, v192
	v_exp_f32_e32 v193, v193
	v_add_f32_e32 v186, 1.0, v186
	v_add_f32_e32 v187, 1.0, v187
	v_add_f32_e32 v188, 1.0, v188
	v_add_f32_e32 v189, 1.0, v189
	v_add_f32_e32 v190, 1.0, v190
	v_add_f32_e32 v191, 1.0, v191
	v_add_f32_e32 v192, 1.0, v192
	v_add_f32_e32 v193, 1.0, v193
	v_rcp_f32_e32 v186, v186
	v_rcp_f32_e32 v187, v187
	v_rcp_f32_e32 v188, v188
	v_rcp_f32_e32 v189, v189
	v_rcp_f32_e32 v190, v190
	v_rcp_f32_e32 v191, v191
	v_rcp_f32_e32 v192, v192
	v_rcp_f32_e32 v193, v193
	v_pk_mul_f32 v[28:29], v[28:29], v[186:187]
	v_pk_mul_f32 v[30:31], v[30:31], v[188:189]
	v_pk_mul_f32 v[24:25], v[24:25], v[190:191]
	v_pk_mul_f32 v[26:27], v[26:27], v[192:193]
	v_cvt_pk_bf16_f32 v28, v28, v29
	v_cvt_pk_bf16_f32 v29, v30, v31
	v_cvt_pk_bf16_f32 v30, v24, v25
	v_cvt_pk_bf16_f32 v31, v26, v27
	global_store_dwordx4 v162, v[28:31], s[100:101]
	s_add_u32 s100, s100, 0x4000
	s_addc_u32 s101, s101, 0
	v_pk_mul_f32 v[12:13], v[12:13], v[160:161] op_sel:[0,1] op_sel_hi:[1,1]
	v_pk_mul_f32 v[14:15], v[14:15], v[160:161] op_sel:[0,1] op_sel_hi:[1,1]
	v_pk_mul_f32 v[8:9], v[8:9], v[160:161] op_sel:[0,1] op_sel_hi:[1,1]
	v_pk_mul_f32 v[10:11], v[10:11], v[160:161] op_sel:[0,1] op_sel_hi:[1,1]
	v_pk_mul_f32 v[4:5], v[4:5], v[160:161] op_sel:[0,1] op_sel_hi:[1,1]
	v_pk_mul_f32 v[6:7], v[6:7], v[160:161] op_sel:[0,1] op_sel_hi:[1,1]
	v_pk_mul_f32 v[0:1], v[0:1], v[160:161] op_sel:[0,1] op_sel_hi:[1,1]
	v_pk_mul_f32 v[2:3], v[2:3], v[160:161] op_sel:[0,1] op_sel_hi:[1,1]
	v_pk_mul_f32 v[186:187], v[4:5], s[4:5]
	v_pk_mul_f32 v[188:189], v[6:7], s[4:5]
	v_pk_mul_f32 v[190:191], v[0:1], s[4:5]
	v_pk_mul_f32 v[192:193], v[2:3], s[4:5]
	v_exp_f32_e32 v186, v186
	v_exp_f32_e32 v187, v187
	v_exp_f32_e32 v188, v188
	v_exp_f32_e32 v189, v189
	v_exp_f32_e32 v190, v190
	v_exp_f32_e32 v191, v191
	v_exp_f32_e32 v192, v192
	v_exp_f32_e32 v193, v193
	v_add_f32_e32 v186, 1.0, v186
	v_add_f32_e32 v187, 1.0, v187
	v_add_f32_e32 v188, 1.0, v188
	v_add_f32_e32 v189, 1.0, v189
	v_add_f32_e32 v190, 1.0, v190
	v_add_f32_e32 v191, 1.0, v191
	v_add_f32_e32 v192, 1.0, v192
	v_add_f32_e32 v193, 1.0, v193
	v_rcp_f32_e32 v186, v186
	v_rcp_f32_e32 v187, v187
	v_rcp_f32_e32 v188, v188
	v_rcp_f32_e32 v189, v189
	v_rcp_f32_e32 v190, v190
	v_rcp_f32_e32 v191, v191
	v_rcp_f32_e32 v192, v192
	v_rcp_f32_e32 v193, v193
	v_pk_mul_f32 v[12:13], v[12:13], v[186:187]
	v_pk_mul_f32 v[14:15], v[14:15], v[188:189]
	v_pk_mul_f32 v[8:9], v[8:9], v[190:191]
	v_pk_mul_f32 v[10:11], v[10:11], v[192:193]
	v_cvt_pk_bf16_f32 v12, v12, v13
	v_cvt_pk_bf16_f32 v13, v14, v15
	v_cvt_pk_bf16_f32 v14, v8, v9
	v_cvt_pk_bf16_f32 v15, v10, v11
	global_store_dwordx4 v162, v[12:15], s[100:101]
	s_branch .Lei_done
.Lei_v:
	s_sub_i32 s7, s30, 8
	v_lshl_add_u32 v163, v150, 5, 0
	v_lshl_add_u32 v163, v149, 3, v163
	v_lshl_add_u32 v162, v163, 1, v162
	s_lshl_b32 s10, s7, 9
	s_add_i32 s10, s10, s6
	s_add_u32 s100, s90, s10
	s_addc_u32 s101, s91, 0
	v_pk_mul_f32 v[124:125], v[124:125], v[154:155] op_sel_hi:[1,0]
	v_pk_mul_f32 v[126:127], v[126:127], v[154:155] op_sel_hi:[1,0]
	v_pk_mul_f32 v[120:121], v[120:121], v[154:155] op_sel_hi:[1,0]
	v_pk_mul_f32 v[122:123], v[122:123], v[154:155] op_sel_hi:[1,0]
	v_pk_mul_f32 v[116:117], v[116:117], v[154:155] op_sel_hi:[1,0]
	v_pk_mul_f32 v[118:119], v[118:119], v[154:155] op_sel_hi:[1,0]
	v_pk_mul_f32 v[112:113], v[112:113], v[154:155] op_sel_hi:[1,0]
	v_pk_mul_f32 v[114:115], v[114:115], v[154:155] op_sel_hi:[1,0]
	v_cvt_pk_bf16_f32 v124, v124, v125
	v_cvt_pk_bf16_f32 v125, v126, v127
	v_cvt_pk_bf16_f32 v126, v120, v121
	v_cvt_pk_bf16_f32 v127, v122, v123
	v_cvt_pk_bf16_f32 v116, v116, v117
	v_cvt_pk_bf16_f32 v117, v118, v119
	v_cvt_pk_bf16_f32 v118, v112, v113
	v_cvt_pk_bf16_f32 v119, v114, v115
	global_store_dwordx4 v162, v[124:127], s[100:101]
	global_store_dwordx4 v162, v[116:119], s[100:101] offset:256
	s_add_u32 s100, s100, 0x4000
	s_addc_u32 s101, s101, 0
	v_pk_mul_f32 v[108:109], v[108:109], v[154:155] op_sel:[0,1] op_sel_hi:[1,1]
	v_pk_mul_f32 v[110:111], v[110:111], v[154:155] op_sel:[0,1] op_sel_hi:[1,1]
	v_pk_mul_f32 v[104:105], v[104:105], v[154:155] op_sel:[0,1] op_sel_hi:[1,1]
	v_pk_mul_f32 v[106:107], v[106:107], v[154:155] op_sel:[0,1] op_sel_hi:[1,1]
	v_pk_mul_f32 v[100:101], v[100:101], v[154:155] op_sel:[0,1] op_sel_hi:[1,1]
	v_pk_mul_f32 v[102:103], v[102:103], v[154:155] op_sel:[0,1] op_sel_hi:[1,1]
	v_pk_mul_f32 v[96:97], v[96:97], v[154:155] op_sel:[0,1] op_sel_hi:[1,1]
	v_pk_mul_f32 v[98:99], v[98:99], v[154:155] op_sel:[0,1] op_sel_hi:[1,1]
	v_cvt_pk_bf16_f32 v108, v108, v109
	v_cvt_pk_bf16_f32 v109, v110, v111
	v_cvt_pk_bf16_f32 v110, v104, v105
	v_cvt_pk_bf16_f32 v111, v106, v107
	v_cvt_pk_bf16_f32 v100, v100, v101
	v_cvt_pk_bf16_f32 v101, v102, v103
	v_cvt_pk_bf16_f32 v102, v96, v97
	v_cvt_pk_bf16_f32 v103, v98, v99
	global_store_dwordx4 v162, v[108:111], s[100:101]
	global_store_dwordx4 v162, v[100:103], s[100:101] offset:256
	s_add_u32 s100, s100, 0x4000
	s_addc_u32 s101, s101, 0
	v_pk_mul_f32 v[92:93], v[92:93], v[156:157] op_sel_hi:[1,0]
	v_pk_mul_f32 v[94:95], v[94:95], v[156:157] op_sel_hi:[1,0]
	v_pk_mul_f32 v[88:89], v[88:89], v[156:157] op_sel_hi:[1,0]
	v_pk_mul_f32 v[90:91], v[90:91], v[156:157] op_sel_hi:[1,0]
	v_pk_mul_f32 v[84:85], v[84:85], v[156:157] op_sel_hi:[1,0]
	v_pk_mul_f32 v[86:87], v[86:87], v[156:157] op_sel_hi:[1,0]
	v_pk_mul_f32 v[80:81], v[80:81], v[156:157] op_sel_hi:[1,0]
	v_pk_mul_f32 v[82:83], v[82:83], v[156:157] op_sel_hi:[1,0]
	v_cvt_pk_bf16_f32 v92, v92, v93
	v_cvt_pk_bf16_f32 v93, v94, v95
	v_cvt_pk_bf16_f32 v94, v88, v89
	v_cvt_pk_bf16_f32 v95, v90, v91
	v_cvt_pk_bf16_f32 v84, v84, v85
	v_cvt_pk_bf16_f32 v85, v86, v87
	v_cvt_pk_bf16_f32 v86, v80, v81
	v_cvt_pk_bf16_f32 v87, v82, v83
	global_store_dwordx4 v162, v[92:95], s[100:101]
	global_store_dwordx4 v162, v[84:87], s[100:101] offset:256
	s_add_u32 s100, s100, 0x4000
	s_addc_u32 s101, s101, 0
	v_pk_mul_f32 v[76:77], v[76:77], v[156:157] op_sel:[0,1] op_sel_hi:[1,1]
	v_pk_mul_f32 v[78:79], v[78:79], v[156:157] op_sel:[0,1] op_sel_hi:[1,1]
	v_pk_mul_f32 v[72:73], v[72:73], v[156:157] op_sel:[0,1] op_sel_hi:[1,1]
	v_pk_mul_f32 v[74:75], v[74:75], v[156:157] op_sel:[0,1] op_sel_hi:[1,1]
	v_pk_mul_f32 v[68:69], v[68:69], v[156:157] op_sel:[0,1] op_sel_hi:[1,1]
	v_pk_mul_f32 v[70:71], v[70:71], v[156:157] op_sel:[0,1] op_sel_hi:[1,1]
	v_pk_mul_f32 v[64:65], v[64:65], v[156:157] op_sel:[0,1] op_sel_hi:[1,1]
	v_pk_mul_f32 v[66:67], v[66:67], v[156:157] op_sel:[0,1] op_sel_hi:[1,1]
	v_cvt_pk_bf16_f32 v76, v76, v77
	v_cvt_pk_bf16_f32 v77, v78, v79
	v_cvt_pk_bf16_f32 v78, v72, v73
	v_cvt_pk_bf16_f32 v79, v74, v75
	v_cvt_pk_bf16_f32 v68, v68, v69
	v_cvt_pk_bf16_f32 v69, v70, v71
	v_cvt_pk_bf16_f32 v70, v64, v65
	v_cvt_pk_bf16_f32 v71, v66, v67
	global_store_dwordx4 v162, v[76:79], s[100:101]
	global_store_dwordx4 v162, v[68:71], s[100:101] offset:256
	s_add_u32 s100, s100, 0x14000
	s_addc_u32 s101, s101, 0
	v_pk_mul_f32 v[60:61], v[60:61], v[158:159] op_sel_hi:[1,0]
	v_pk_mul_f32 v[62:63], v[62:63], v[158:159] op_sel_hi:[1,0]
	v_pk_mul_f32 v[56:57], v[56:57], v[158:159] op_sel_hi:[1,0]
	v_pk_mul_f32 v[58:59], v[58:59], v[158:159] op_sel_hi:[1,0]
	v_pk_mul_f32 v[52:53], v[52:53], v[158:159] op_sel_hi:[1,0]
	v_pk_mul_f32 v[54:55], v[54:55], v[158:159] op_sel_hi:[1,0]
	v_pk_mul_f32 v[48:49], v[48:49], v[158:159] op_sel_hi:[1,0]
	v_pk_mul_f32 v[50:51], v[50:51], v[158:159] op_sel_hi:[1,0]
	v_cvt_pk_bf16_f32 v60, v60, v61
	v_cvt_pk_bf16_f32 v61, v62, v63
	v_cvt_pk_bf16_f32 v62, v56, v57
	v_cvt_pk_bf16_f32 v63, v58, v59
	v_cvt_pk_bf16_f32 v52, v52, v53
	v_cvt_pk_bf16_f32 v53, v54, v55
	v_cvt_pk_bf16_f32 v54, v48, v49
	v_cvt_pk_bf16_f32 v55, v50, v51
	global_store_dwordx4 v162, v[60:63], s[100:101]
	global_store_dwordx4 v162, v[52:55], s[100:101] offset:256
	s_add_u32 s100, s100, 0x4000
	s_addc_u32 s101, s101, 0
	v_pk_mul_f32 v[44:45], v[44:45], v[158:159] op_sel:[0,1] op_sel_hi:[1,1]
	v_pk_mul_f32 v[46:47], v[46:47], v[158:159] op_sel:[0,1] op_sel_hi:[1,1]
	v_pk_mul_f32 v[40:41], v[40:41], v[158:159] op_sel:[0,1] op_sel_hi:[1,1]
	v_pk_mul_f32 v[42:43], v[42:43], v[158:159] op_sel:[0,1] op_sel_hi:[1,1]
	v_pk_mul_f32 v[36:37], v[36:37], v[158:159] op_sel:[0,1] op_sel_hi:[1,1]
	v_pk_mul_f32 v[38:39], v[38:39], v[158:159] op_sel:[0,1] op_sel_hi:[1,1]
	v_pk_mul_f32 v[32:33], v[32:33], v[158:159] op_sel:[0,1] op_sel_hi:[1,1]
	v_pk_mul_f32 v[34:35], v[34:35], v[158:159] op_sel:[0,1] op_sel_hi:[1,1]
	v_cvt_pk_bf16_f32 v44, v44, v45
	v_cvt_pk_bf16_f32 v45, v46, v47
	v_cvt_pk_bf16_f32 v46, v40, v41
	v_cvt_pk_bf16_f32 v47, v42, v43
	v_cvt_pk_bf16_f32 v36, v36, v37
	v_cvt_pk_bf16_f32 v37, v38, v39
	v_cvt_pk_bf16_f32 v38, v32, v33
	v_cvt_pk_bf16_f32 v39, v34, v35
	global_store_dwordx4 v162, v[44:47], s[100:101]
	global_store_dwordx4 v162, v[36:39], s[100:101] offset:256
	s_add_u32 s100, s100, 0x4000
	s_addc_u32 s101, s101, 0
	v_pk_mul_f32 v[28:29], v[28:29], v[160:161] op_sel_hi:[1,0]
	v_pk_mul_f32 v[30:31], v[30:31], v[160:161] op_sel_hi:[1,0]
	v_pk_mul_f32 v[24:25], v[24:25], v[160:161] op_sel_hi:[1,0]
	v_pk_mul_f32 v[26:27], v[26:27], v[160:161] op_sel_hi:[1,0]
	v_pk_mul_f32 v[20:21], v[20:21], v[160:161] op_sel_hi:[1,0]
	v_pk_mul_f32 v[22:23], v[22:23], v[160:161] op_sel_hi:[1,0]
	v_pk_mul_f32 v[16:17], v[16:17], v[160:161] op_sel_hi:[1,0]
	v_pk_mul_f32 v[18:19], v[18:19], v[160:161] op_sel_hi:[1,0]
	v_cvt_pk_bf16_f32 v28, v28, v29
	v_cvt_pk_bf16_f32 v29, v30, v31
	v_cvt_pk_bf16_f32 v30, v24, v25
	v_cvt_pk_bf16_f32 v31, v26, v27
	v_cvt_pk_bf16_f32 v20, v20, v21
	v_cvt_pk_bf16_f32 v21, v22, v23
	v_cvt_pk_bf16_f32 v22, v16, v17
	v_cvt_pk_bf16_f32 v23, v18, v19
	global_store_dwordx4 v162, v[28:31], s[100:101]
	global_store_dwordx4 v162, v[20:23], s[100:101] offset:256
	s_add_u32 s100, s100, 0x4000
	s_addc_u32 s101, s101, 0
	v_pk_mul_f32 v[12:13], v[12:13], v[160:161] op_sel:[0,1] op_sel_hi:[1,1]
	v_pk_mul_f32 v[14:15], v[14:15], v[160:161] op_sel:[0,1] op_sel_hi:[1,1]
	v_pk_mul_f32 v[8:9], v[8:9], v[160:161] op_sel:[0,1] op_sel_hi:[1,1]
	v_pk_mul_f32 v[10:11], v[10:11], v[160:161] op_sel:[0,1] op_sel_hi:[1,1]
	v_pk_mul_f32 v[4:5], v[4:5], v[160:161] op_sel:[0,1] op_sel_hi:[1,1]
	v_pk_mul_f32 v[6:7], v[6:7], v[160:161] op_sel:[0,1] op_sel_hi:[1,1]
	v_pk_mul_f32 v[0:1], v[0:1], v[160:161] op_sel:[0,1] op_sel_hi:[1,1]
	v_pk_mul_f32 v[2:3], v[2:3], v[160:161] op_sel:[0,1] op_sel_hi:[1,1]
	v_cvt_pk_bf16_f32 v12, v12, v13
	v_cvt_pk_bf16_f32 v13, v14, v15
	v_cvt_pk_bf16_f32 v14, v8, v9
	v_cvt_pk_bf16_f32 v15, v10, v11
	v_cvt_pk_bf16_f32 v4, v4, v5
	v_cvt_pk_bf16_f32 v5, v6, v7
	v_cvt_pk_bf16_f32 v6, v0, v1
	v_cvt_pk_bf16_f32 v7, v2, v3
	global_store_dwordx4 v162, v[12:15], s[100:101]
	global_store_dwordx4 v162, v[4:7], s[100:101] offset:256
	s_branch .Lei_done
.Lei_rope:
	s_sub_i32 s7, s30, 4
	s_lshr_b32 s10, s7, 1
	s_and_b32 s11, s7, 1
	s_cmp_eq_u32 s10, 0
	s_cselect_b32 s98, s38, s50
	s_cselect_b32 s99, s39, s51
	s_cselect_b32 s26, 1.0, 0x3db504f3
	s_mov_b32 s27, s26
	v_and_b32_e32 v163, 1, v150
	v_lshlrev_b32_e32 v163, 5, v163
	v_lshl_add_u32 v163, v149, 3, v163
	v_lshrrev_b32_e32 v237, 1, v150
	v_lshl_add_u32 v237, v237, 7, v163
	v_lshl_add_u32 v162, v237, 1, v162
	v_lshlrev_b32_e32 v163, 3, v163
	v_lshl_add_u32 v163, v152, 9, v163
	s_lshl_b32 s10, s11, 9
	s_add_i32 s10, s10, s6
	s_add_u32 s100, s98, s10
	s_addc_u32 s101, s99, 0
	s_and_b32 s7, s31, 7
	s_lshl_b32 s7, s7, 17
	s_add_u32 s98, s52, s7
	s_addc_u32 s99, s53, 0
	s_add_u32 s28, s98, 0x0
	s_addc_u32 s29, s99, 0
	global_load_dwordx4 v[170:173], v163, s[28:29]
	global_load_dwordx4 v[174:177], v163, s[28:29] offset:16
	global_load_dwordx4 v[178:181], v163, s[28:29] offset:32
	global_load_dwordx4 v[182:185], v163, s[28:29] offset:48
	s_add_u32 s28, s98, 0x2000
	s_addc_u32 s29, s99, 0
	global_load_dwordx4 v[186:189], v163, s[28:29]
	global_load_dwordx4 v[190:193], v163, s[28:29] offset:16
	global_load_dwordx4 v[194:197], v163, s[28:29] offset:32
	global_load_dwordx4 v[198:201], v163, s[28:29] offset:48
	v_pk_mul_f32 v[124:125], v[124:125], v[154:155] op_sel_hi:[1,0]
	v_pk_mul_f32 v[126:127], v[126:127], v[154:155] op_sel_hi:[1,0]
	v_pk_mul_f32 v[120:121], v[120:121], v[154:155] op_sel_hi:[1,0]
	v_pk_mul_f32 v[122:123], v[122:123], v[154:155] op_sel_hi:[1,0]
	v_pk_mul_f32 v[116:117], v[116:117], v[154:155] op_sel_hi:[1,0]
	v_pk_mul_f32 v[118:119], v[118:119], v[154:155] op_sel_hi:[1,0]
	v_pk_mul_f32 v[112:113], v[112:113], v[154:155] op_sel_hi:[1,0]
	v_pk_mul_f32 v[114:115], v[114:115], v[154:155] op_sel_hi:[1,0]
	s_waitcnt vmcnt(4)
	v_mul_f32_e32 v236, v116, v171
	v_mul_f32_e32 v237, v124, v171
	v_fma_f32 v124, v124, v170, -v236
	v_fma_f32 v116, v116, v170, v237
	v_mul_f32_e32 v236, v117, v173
	v_mul_f32_e32 v237, v125, v173
	v_fma_f32 v125, v125, v172, -v236
	v_fma_f32 v117, v117, v172, v237
	v_mul_f32_e32 v236, v118, v175
	v_mul_f32_e32 v237, v126, v175
	v_fma_f32 v126, v126, v174, -v236
	v_fma_f32 v118, v118, v174, v237
	v_mul_f32_e32 v236, v119, v177
	v_mul_f32_e32 v237, v127, v177
	v_fma_f32 v127, v127, v176, -v236
	v_fma_f32 v119, v119, v176, v237
	v_mul_f32_e32 v236, v112, v179
	v_mul_f32_e32 v237, v120, v179
	v_fma_f32 v120, v120, v178, -v236
	v_fma_f32 v112, v112, v178, v237
	v_mul_f32_e32 v236, v113, v181
	v_mul_f32_e32 v237, v121, v181
	v_fma_f32 v121, v121, v180, -v236
	v_fma_f32 v113, v113, v180, v237
	v_mul_f32_e32 v236, v114, v183
	v_mul_f32_e32 v237, v122, v183
	v_fma_f32 v122, v122, v182, -v236
	v_fma_f32 v114, v114, v182, v237
	v_mul_f32_e32 v236, v115, v185
	v_mul_f32_e32 v237, v123, v185
	v_fma_f32 v123, v123, v184, -v236
	v_fma_f32 v115, v115, v184, v237
	v_pk_mul_f32 v[124:125], v[124:125], s[26:27]
	v_pk_mul_f32 v[126:127], v[126:127], s[26:27]
	v_pk_mul_f32 v[120:121], v[120:121], s[26:27]
	v_pk_mul_f32 v[122:123], v[122:123], s[26:27]
	v_pk_mul_f32 v[116:117], v[116:117], s[26:27]
	v_pk_mul_f32 v[118:119], v[118:119], s[26:27]
	v_pk_mul_f32 v[112:113], v[112:113], s[26:27]
	v_pk_mul_f32 v[114:115], v[114:115], s[26:27]
	v_cvt_pk_bf16_f32 v124, v124, v125
	v_cvt_pk_bf16_f32 v125, v126, v127
	v_cvt_pk_bf16_f32 v126, v120, v121
	v_cvt_pk_bf16_f32 v127, v122, v123
	v_cvt_pk_bf16_f32 v116, v116, v117
	v_cvt_pk_bf16_f32 v117, v118, v119
	v_cvt_pk_bf16_f32 v118, v112, v113
	v_cvt_pk_bf16_f32 v119, v114, v115
	global_store_dwordx4 v162, v[124:127], s[100:101]
	global_store_dwordx4 v162, v[116:119], s[100:101] offset:128
	s_add_u32 s100, s100, 0x4000
	s_addc_u32 s101, s101, 0
	s_add_u32 s28, s98, 0x4000
	s_addc_u32 s29, s99, 0
	global_load_dwordx4 v[170:173], v163, s[28:29]
	global_load_dwordx4 v[174:177], v163, s[28:29] offset:16
	global_load_dwordx4 v[178:181], v163, s[28:29] offset:32
	global_load_dwordx4 v[182:185], v163, s[28:29] offset:48
	v_pk_mul_f32 v[108:109], v[108:109], v[154:155] op_sel:[0,1] op_sel_hi:[1,1]
	v_pk_mul_f32 v[110:111], v[110:111], v[154:155] op_sel:[0,1] op_sel_hi:[1,1]
	v_pk_mul_f32 v[104:105], v[104:105], v[154:155] op_sel:[0,1] op_sel_hi:[1,1]
	v_pk_mul_f32 v[106:107], v[106:107], v[154:155] op_sel:[0,1] op_sel_hi:[1,1]
	v_pk_mul_f32 v[100:101], v[100:101], v[154:155] op_sel:[0,1] op_sel_hi:[1,1]
	v_pk_mul_f32 v[102:103], v[102:103], v[154:155] op_sel:[0,1] op_sel_hi:[1,1]
	v_pk_mul_f32 v[96:97], v[96:97], v[154:155] op_sel:[0,1] op_sel_hi:[1,1]
	v_pk_mul_f32 v[98:99], v[98:99], v[154:155] op_sel:[0,1] op_sel_hi:[1,1]
	s_waitcnt vmcnt(6)
	v_mul_f32_e32 v236, v100, v187
	v_mul_f32_e32 v237, v108, v187
	v_fma_f32 v108, v108, v186, -v236
	v_fma_f32 v100, v100, v186, v237
	v_mul_f32_e32 v236, v101, v189
	v_mul_f32_e32 v237, v109, v189
	v_fma_f32 v109, v109, v188, -v236
	v_fma_f32 v101, v101, v188, v237
	v_mul_f32_e32 v236, v102, v191
	v_mul_f32_e32 v237, v110, v191
	v_fma_f32 v110, v110, v190, -v236
	v_fma_f32 v102, v102, v190, v237
	v_mul_f32_e32 v236, v103, v193
	v_mul_f32_e32 v237, v111, v193
	v_fma_f32 v111, v111, v192, -v236
	v_fma_f32 v103, v103, v192, v237
	v_mul_f32_e32 v236, v96, v195
	v_mul_f32_e32 v237, v104, v195
	v_fma_f32 v104, v104, v194, -v236
	v_fma_f32 v96, v96, v194, v237
	v_mul_f32_e32 v236, v97, v197
	v_mul_f32_e32 v237, v105, v197
	v_fma_f32 v105, v105, v196, -v236
	v_fma_f32 v97, v97, v196, v237
	v_mul_f32_e32 v236, v98, v199
	v_mul_f32_e32 v237, v106, v199
	v_fma_f32 v106, v106, v198, -v236
	v_fma_f32 v98, v98, v198, v237
	v_mul_f32_e32 v236, v99, v201
	v_mul_f32_e32 v237, v107, v201
	v_fma_f32 v107, v107, v200, -v236
	v_fma_f32 v99, v99, v200, v237
	v_pk_mul_f32 v[108:109], v[108:109], s[26:27]
	v_pk_mul_f32 v[110:111], v[110:111], s[26:27]
	v_pk_mul_f32 v[104:105], v[104:105], s[26:27]
	v_pk_mul_f32 v[106:107], v[106:107], s[26:27]
	v_pk_mul_f32 v[100:101], v[100:101], s[26:27]
	v_pk_mul_f32 v[102:103], v[102:103], s[26:27]
	v_pk_mul_f32 v[96:97], v[96:97], s[26:27]
	v_pk_mul_f32 v[98:99], v[98:99], s[26:27]
	v_cvt_pk_bf16_f32 v108, v108, v109
	v_cvt_pk_bf16_f32 v109, v110, v111
	v_cvt_pk_bf16_f32 v110, v104, v105
	v_cvt_pk_bf16_f32 v111, v106, v107
	v_cvt_pk_bf16_f32 v100, v100, v101
	v_cvt_pk_bf16_f32 v101, v102, v103
	v_cvt_pk_bf16_f32 v102, v96, v97
	v_cvt_pk_bf16_f32 v103, v98, v99
	global_store_dwordx4 v162, v[108:111], s[100:101]
	global_store_dwordx4 v162, v[100:103], s[100:101] offset:128
	s_add_u32 s100, s100, 0x4000
	s_addc_u32 s101, s101, 0
	s_add_u32 s28, s98, 0x6000
	s_addc_u32 s29, s99, 0
	global_load_dwordx4 v[186:189], v163, s[28:29]
	global_load_dwordx4 v[190:193], v163, s[28:29] offset:16
	global_load_dwordx4 v[194:197], v163, s[28:29] offset:32
	global_load_dwordx4 v[198:201], v163, s[28:29] offset:48
	v_pk_mul_f32 v[92:93], v[92:93], v[156:157] op_sel_hi:[1,0]
	v_pk_mul_f32 v[94:95], v[94:95], v[156:157] op_sel_hi:[1,0]
	v_pk_mul_f32 v[88:89], v[88:89], v[156:157] op_sel_hi:[1,0]
	v_pk_mul_f32 v[90:91], v[90:91], v[156:157] op_sel_hi:[1,0]
	v_pk_mul_f32 v[84:85], v[84:85], v[156:157] op_sel_hi:[1,0]
	v_pk_mul_f32 v[86:87], v[86:87], v[156:157] op_sel_hi:[1,0]
	v_pk_mul_f32 v[80:81], v[80:81], v[156:157] op_sel_hi:[1,0]
	v_pk_mul_f32 v[82:83], v[82:83], v[156:157] op_sel_hi:[1,0]
	s_waitcnt vmcnt(6)
	v_mul_f32_e32 v236, v84, v171
	v_mul_f32_e32 v237, v92, v171
	v_fma_f32 v92, v92, v170, -v236
	v_fma_f32 v84, v84, v170, v237
	v_mul_f32_e32 v236, v85, v173
	v_mul_f32_e32 v237, v93, v173
	v_fma_f32 v93, v93, v172, -v236
	v_fma_f32 v85, v85, v172, v237
	v_mul_f32_e32 v236, v86, v175
	v_mul_f32_e32 v237, v94, v175
	v_fma_f32 v94, v94, v174, -v236
	v_fma_f32 v86, v86, v174, v237
	v_mul_f32_e32 v236, v87, v177
	v_mul_f32_e32 v237, v95, v177
	v_fma_f32 v95, v95, v176, -v236
	v_fma_f32 v87, v87, v176, v237
	v_mul_f32_e32 v236, v80, v179
	v_mul_f32_e32 v237, v88, v179
	v_fma_f32 v88, v88, v178, -v236
	v_fma_f32 v80, v80, v178, v237
	v_mul_f32_e32 v236, v81, v181
	v_mul_f32_e32 v237, v89, v181
	v_fma_f32 v89, v89, v180, -v236
	v_fma_f32 v81, v81, v180, v237
	v_mul_f32_e32 v236, v82, v183
	v_mul_f32_e32 v237, v90, v183
	v_fma_f32 v90, v90, v182, -v236
	v_fma_f32 v82, v82, v182, v237
	v_mul_f32_e32 v236, v83, v185
	v_mul_f32_e32 v237, v91, v185
	v_fma_f32 v91, v91, v184, -v236
	v_fma_f32 v83, v83, v184, v237
	v_pk_mul_f32 v[92:93], v[92:93], s[26:27]
	v_pk_mul_f32 v[94:95], v[94:95], s[26:27]
	v_pk_mul_f32 v[88:89], v[88:89], s[26:27]
	v_pk_mul_f32 v[90:91], v[90:91], s[26:27]
	v_pk_mul_f32 v[84:85], v[84:85], s[26:27]
	v_pk_mul_f32 v[86:87], v[86:87], s[26:27]
	v_pk_mul_f32 v[80:81], v[80:81], s[26:27]
	v_pk_mul_f32 v[82:83], v[82:83], s[26:27]
	v_cvt_pk_bf16_f32 v92, v92, v93
	v_cvt_pk_bf16_f32 v93, v94, v95
	v_cvt_pk_bf16_f32 v94, v88, v89
	v_cvt_pk_bf16_f32 v95, v90, v91
	v_cvt_pk_bf16_f32 v84, v84, v85
	v_cvt_pk_bf16_f32 v85, v86, v87
	v_cvt_pk_bf16_f32 v86, v80, v81
	v_cvt_pk_bf16_f32 v87, v82, v83
	global_store_dwordx4 v162, v[92:95], s[100:101]
	global_store_dwordx4 v162, v[84:87], s[100:101] offset:128
	s_add_u32 s100, s100, 0x4000
	s_addc_u32 s101, s101, 0
	s_add_u32 s28, s98, 0x10000
	s_addc_u32 s29, s99, 0
	global_load_dwordx4 v[170:173], v163, s[28:29]
	global_load_dwordx4 v[174:177], v163, s[28:29] offset:16
	global_load_dwordx4 v[178:181], v163, s[28:29] offset:32
	global_load_dwordx4 v[182:185], v163, s[28:29] offset:48
	v_pk_mul_f32 v[76:77], v[76:77], v[156:157] op_sel:[0,1] op_sel_hi:[1,1]
	v_pk_mul_f32 v[78:79], v[78:79], v[156:157] op_sel:[0,1] op_sel_hi:[1,1]
	v_pk_mul_f32 v[72:73], v[72:73], v[156:157] op_sel:[0,1] op_sel_hi:[1,1]
	v_pk_mul_f32 v[74:75], v[74:75], v[156:157] op_sel:[0,1] op_sel_hi:[1,1]
	v_pk_mul_f32 v[68:69], v[68:69], v[156:157] op_sel:[0,1] op_sel_hi:[1,1]
	v_pk_mul_f32 v[70:71], v[70:71], v[156:157] op_sel:[0,1] op_sel_hi:[1,1]
	v_pk_mul_f32 v[64:65], v[64:65], v[156:157] op_sel:[0,1] op_sel_hi:[1,1]
	v_pk_mul_f32 v[66:67], v[66:67], v[156:157] op_sel:[0,1] op_sel_hi:[1,1]
	s_waitcnt vmcnt(6)
	v_mul_f32_e32 v236, v68, v187
	v_mul_f32_e32 v237, v76, v187
	v_fma_f32 v76, v76, v186, -v236
	v_fma_f32 v68, v68, v186, v237
	v_mul_f32_e32 v236, v69, v189
	v_mul_f32_e32 v237, v77, v189
	v_fma_f32 v77, v77, v188, -v236
	v_fma_f32 v69, v69, v188, v237
	v_mul_f32_e32 v236, v70, v191
	v_mul_f32_e32 v237, v78, v191
	v_fma_f32 v78, v78, v190, -v236
	v_fma_f32 v70, v70, v190, v237
	v_mul_f32_e32 v236, v71, v193
	v_mul_f32_e32 v237, v79, v193
	v_fma_f32 v79, v79, v192, -v236
	v_fma_f32 v71, v71, v192, v237
	v_mul_f32_e32 v236, v64, v195
	v_mul_f32_e32 v237, v72, v195
	v_fma_f32 v72, v72, v194, -v236
	v_fma_f32 v64, v64, v194, v237
	v_mul_f32_e32 v236, v65, v197
	v_mul_f32_e32 v237, v73, v197
	v_fma_f32 v73, v73, v196, -v236
	v_fma_f32 v65, v65, v196, v237
	v_mul_f32_e32 v236, v66, v199
	v_mul_f32_e32 v237, v74, v199
	v_fma_f32 v74, v74, v198, -v236
	v_fma_f32 v66, v66, v198, v237
	v_mul_f32_e32 v236, v67, v201
	v_mul_f32_e32 v237, v75, v201
	v_fma_f32 v75, v75, v200, -v236
	v_fma_f32 v67, v67, v200, v237
	v_pk_mul_f32 v[76:77], v[76:77], s[26:27]
	v_pk_mul_f32 v[78:79], v[78:79], s[26:27]
	v_pk_mul_f32 v[72:73], v[72:73], s[26:27]
	v_pk_mul_f32 v[74:75], v[74:75], s[26:27]
	v_pk_mul_f32 v[68:69], v[68:69], s[26:27]
	v_pk_mul_f32 v[70:71], v[70:71], s[26:27]
	v_pk_mul_f32 v[64:65], v[64:65], s[26:27]
	v_pk_mul_f32 v[66:67], v[66:67], s[26:27]
	v_cvt_pk_bf16_f32 v76, v76, v77
	v_cvt_pk_bf16_f32 v77, v78, v79
	v_cvt_pk_bf16_f32 v78, v72, v73
	v_cvt_pk_bf16_f32 v79, v74, v75
	v_cvt_pk_bf16_f32 v68, v68, v69
	v_cvt_pk_bf16_f32 v69, v70, v71
	v_cvt_pk_bf16_f32 v70, v64, v65
	v_cvt_pk_bf16_f32 v71, v66, v67
	global_store_dwordx4 v162, v[76:79], s[100:101]
	global_store_dwordx4 v162, v[68:71], s[100:101] offset:128
	s_add_u32 s100, s100, 0x14000
	s_addc_u32 s101, s101, 0
	s_add_u32 s28, s98, 0x12000
	s_addc_u32 s29, s99, 0
	global_load_dwordx4 v[186:189], v163, s[28:29]
	global_load_dwordx4 v[190:193], v163, s[28:29] offset:16
	global_load_dwordx4 v[194:197], v163, s[28:29] offset:32
	global_load_dwordx4 v[198:201], v163, s[28:29] offset:48
	v_pk_mul_f32 v[60:61], v[60:61], v[158:159] op_sel_hi:[1,0]
	v_pk_mul_f32 v[62:63], v[62:63], v[158:159] op_sel_hi:[1,0]
	v_pk_mul_f32 v[56:57], v[56:57], v[158:159] op_sel_hi:[1,0]
	v_pk_mul_f32 v[58:59], v[58:59], v[158:159] op_sel_hi:[1,0]
	v_pk_mul_f32 v[52:53], v[52:53], v[158:159] op_sel_hi:[1,0]
	v_pk_mul_f32 v[54:55], v[54:55], v[158:159] op_sel_hi:[1,0]
	v_pk_mul_f32 v[48:49], v[48:49], v[158:159] op_sel_hi:[1,0]
	v_pk_mul_f32 v[50:51], v[50:51], v[158:159] op_sel_hi:[1,0]
	s_waitcnt vmcnt(6)
	v_mul_f32_e32 v236, v52, v171
	v_mul_f32_e32 v237, v60, v171
	v_fma_f32 v60, v60, v170, -v236
	v_fma_f32 v52, v52, v170, v237
	v_mul_f32_e32 v236, v53, v173
	v_mul_f32_e32 v237, v61, v173
	v_fma_f32 v61, v61, v172, -v236
	v_fma_f32 v53, v53, v172, v237
	v_mul_f32_e32 v236, v54, v175
	v_mul_f32_e32 v237, v62, v175
	v_fma_f32 v62, v62, v174, -v236
	v_fma_f32 v54, v54, v174, v237
	v_mul_f32_e32 v236, v55, v177
	v_mul_f32_e32 v237, v63, v177
	v_fma_f32 v63, v63, v176, -v236
	v_fma_f32 v55, v55, v176, v237
	v_mul_f32_e32 v236, v48, v179
	v_mul_f32_e32 v237, v56, v179
	v_fma_f32 v56, v56, v178, -v236
	v_fma_f32 v48, v48, v178, v237
	v_mul_f32_e32 v236, v49, v181
	v_mul_f32_e32 v237, v57, v181
	v_fma_f32 v57, v57, v180, -v236
	v_fma_f32 v49, v49, v180, v237
	v_mul_f32_e32 v236, v50, v183
	v_mul_f32_e32 v237, v58, v183
	v_fma_f32 v58, v58, v182, -v236
	v_fma_f32 v50, v50, v182, v237
	v_mul_f32_e32 v236, v51, v185
	v_mul_f32_e32 v237, v59, v185
	v_fma_f32 v59, v59, v184, -v236
	v_fma_f32 v51, v51, v184, v237
	v_pk_mul_f32 v[60:61], v[60:61], s[26:27]
	v_pk_mul_f32 v[62:63], v[62:63], s[26:27]
	v_pk_mul_f32 v[56:57], v[56:57], s[26:27]
	v_pk_mul_f32 v[58:59], v[58:59], s[26:27]
	v_pk_mul_f32 v[52:53], v[52:53], s[26:27]
	v_pk_mul_f32 v[54:55], v[54:55], s[26:27]
	v_pk_mul_f32 v[48:49], v[48:49], s[26:27]
	v_pk_mul_f32 v[50:51], v[50:51], s[26:27]
	v_cvt_pk_bf16_f32 v60, v60, v61
	v_cvt_pk_bf16_f32 v61, v62, v63
	v_cvt_pk_bf16_f32 v62, v56, v57
	v_cvt_pk_bf16_f32 v63, v58, v59
	v_cvt_pk_bf16_f32 v52, v52, v53
	v_cvt_pk_bf16_f32 v53, v54, v55
	v_cvt_pk_bf16_f32 v54, v48, v49
	v_cvt_pk_bf16_f32 v55, v50, v51
	global_store_dwordx4 v162, v[60:63], s[100:101]
	global_store_dwordx4 v162, v[52:55], s[100:101] offset:128
	s_add_u32 s100, s100, 0x4000
	s_addc_u32 s101, s101, 0
	s_add_u32 s28, s98, 0x14000
	s_addc_u32 s29, s99, 0
	global_load_dwordx4 v[170:173], v163, s[28:29]
	global_load_dwordx4 v[174:177], v163, s[28:29] offset:16
	global_load_dwordx4 v[178:181], v163, s[28:29] offset:32
	global_load_dwordx4 v[182:185], v163, s[28:29] offset:48
	v_pk_mul_f32 v[44:45], v[44:45], v[158:159] op_sel:[0,1] op_sel_hi:[1,1]
	v_pk_mul_f32 v[46:47], v[46:47], v[158:159] op_sel:[0,1] op_sel_hi:[1,1]
	v_pk_mul_f32 v[40:41], v[40:41], v[158:159] op_sel:[0,1] op_sel_hi:[1,1]
	v_pk_mul_f32 v[42:43], v[42:43], v[158:159] op_sel:[0,1] op_sel_hi:[1,1]
	v_pk_mul_f32 v[36:37], v[36:37], v[158:159] op_sel:[0,1] op_sel_hi:[1,1]
	v_pk_mul_f32 v[38:39], v[38:39], v[158:159] op_sel:[0,1] op_sel_hi:[1,1]
	v_pk_mul_f32 v[32:33], v[32:33], v[158:159] op_sel:[0,1] op_sel_hi:[1,1]
	v_pk_mul_f32 v[34:35], v[34:35], v[158:159] op_sel:[0,1] op_sel_hi:[1,1]
	s_waitcnt vmcnt(6)
	v_mul_f32_e32 v236, v36, v187
	v_mul_f32_e32 v237, v44, v187
	v_fma_f32 v44, v44, v186, -v236
	v_fma_f32 v36, v36, v186, v237
	v_mul_f32_e32 v236, v37, v189
	v_mul_f32_e32 v237, v45, v189
	v_fma_f32 v45, v45, v188, -v236
	v_fma_f32 v37, v37, v188, v237
	v_mul_f32_e32 v236, v38, v191
	v_mul_f32_e32 v237, v46, v191
	v_fma_f32 v46, v46, v190, -v236
	v_fma_f32 v38, v38, v190, v237
	v_mul_f32_e32 v236, v39, v193
	v_mul_f32_e32 v237, v47, v193
	v_fma_f32 v47, v47, v192, -v236
	v_fma_f32 v39, v39, v192, v237
	v_mul_f32_e32 v236, v32, v195
	v_mul_f32_e32 v237, v40, v195
	v_fma_f32 v40, v40, v194, -v236
	v_fma_f32 v32, v32, v194, v237
	v_mul_f32_e32 v236, v33, v197
	v_mul_f32_e32 v237, v41, v197
	v_fma_f32 v41, v41, v196, -v236
	v_fma_f32 v33, v33, v196, v237
	v_mul_f32_e32 v236, v34, v199
	v_mul_f32_e32 v237, v42, v199
	v_fma_f32 v42, v42, v198, -v236
	v_fma_f32 v34, v34, v198, v237
	v_mul_f32_e32 v236, v35, v201
	v_mul_f32_e32 v237, v43, v201
	v_fma_f32 v43, v43, v200, -v236
	v_fma_f32 v35, v35, v200, v237
	v_pk_mul_f32 v[44:45], v[44:45], s[26:27]
	v_pk_mul_f32 v[46:47], v[46:47], s[26:27]
	v_pk_mul_f32 v[40:41], v[40:41], s[26:27]
	v_pk_mul_f32 v[42:43], v[42:43], s[26:27]
	v_pk_mul_f32 v[36:37], v[36:37], s[26:27]
	v_pk_mul_f32 v[38:39], v[38:39], s[26:27]
	v_pk_mul_f32 v[32:33], v[32:33], s[26:27]
	v_pk_mul_f32 v[34:35], v[34:35], s[26:27]
	v_cvt_pk_bf16_f32 v44, v44, v45
	v_cvt_pk_bf16_f32 v45, v46, v47
	v_cvt_pk_bf16_f32 v46, v40, v41
	v_cvt_pk_bf16_f32 v47, v42, v43
	v_cvt_pk_bf16_f32 v36, v36, v37
	v_cvt_pk_bf16_f32 v37, v38, v39
	v_cvt_pk_bf16_f32 v38, v32, v33
	v_cvt_pk_bf16_f32 v39, v34, v35
	global_store_dwordx4 v162, v[44:47], s[100:101]
	global_store_dwordx4 v162, v[36:39], s[100:101] offset:128
	s_add_u32 s100, s100, 0x4000
	s_addc_u32 s101, s101, 0
	s_add_u32 s28, s98, 0x16000
	s_addc_u32 s29, s99, 0
	global_load_dwordx4 v[186:189], v163, s[28:29]
	global_load_dwordx4 v[190:193], v163, s[28:29] offset:16
	global_load_dwordx4 v[194:197], v163, s[28:29] offset:32
	global_load_dwordx4 v[198:201], v163, s[28:29] offset:48
	v_pk_mul_f32 v[28:29], v[28:29], v[160:161] op_sel_hi:[1,0]
	v_pk_mul_f32 v[30:31], v[30:31], v[160:161] op_sel_hi:[1,0]
	v_pk_mul_f32 v[24:25], v[24:25], v[160:161] op_sel_hi:[1,0]
	v_pk_mul_f32 v[26:27], v[26:27], v[160:161] op_sel_hi:[1,0]
	v_pk_mul_f32 v[20:21], v[20:21], v[160:161] op_sel_hi:[1,0]
	v_pk_mul_f32 v[22:23], v[22:23], v[160:161] op_sel_hi:[1,0]
	v_pk_mul_f32 v[16:17], v[16:17], v[160:161] op_sel_hi:[1,0]
	v_pk_mul_f32 v[18:19], v[18:19], v[160:161] op_sel_hi:[1,0]
	s_waitcnt vmcnt(6)
	v_mul_f32_e32 v236, v20, v171
	v_mul_f32_e32 v237, v28, v171
	v_fma_f32 v28, v28, v170, -v236
	v_fma_f32 v20, v20, v170, v237
	v_mul_f32_e32 v236, v21, v173
	v_mul_f32_e32 v237, v29, v173
	v_fma_f32 v29, v29, v172, -v236
	v_fma_f32 v21, v21, v172, v237
	v_mul_f32_e32 v236, v22, v175
	v_mul_f32_e32 v237, v30, v175
	v_fma_f32 v30, v30, v174, -v236
	v_fma_f32 v22, v22, v174, v237
	v_mul_f32_e32 v236, v23, v177
	v_mul_f32_e32 v237, v31, v177
	v_fma_f32 v31, v31, v176, -v236
	v_fma_f32 v23, v23, v176, v237
	v_mul_f32_e32 v236, v16, v179
	v_mul_f32_e32 v237, v24, v179
	v_fma_f32 v24, v24, v178, -v236
	v_fma_f32 v16, v16, v178, v237
	v_mul_f32_e32 v236, v17, v181
	v_mul_f32_e32 v237, v25, v181
	v_fma_f32 v25, v25, v180, -v236
	v_fma_f32 v17, v17, v180, v237
	v_mul_f32_e32 v236, v18, v183
	v_mul_f32_e32 v237, v26, v183
	v_fma_f32 v26, v26, v182, -v236
	v_fma_f32 v18, v18, v182, v237
	v_mul_f32_e32 v236, v19, v185
	v_mul_f32_e32 v237, v27, v185
	v_fma_f32 v27, v27, v184, -v236
	v_fma_f32 v19, v19, v184, v237
	v_pk_mul_f32 v[28:29], v[28:29], s[26:27]
	v_pk_mul_f32 v[30:31], v[30:31], s[26:27]
	v_pk_mul_f32 v[24:25], v[24:25], s[26:27]
	v_pk_mul_f32 v[26:27], v[26:27], s[26:27]
	v_pk_mul_f32 v[20:21], v[20:21], s[26:27]
	v_pk_mul_f32 v[22:23], v[22:23], s[26:27]
	v_pk_mul_f32 v[16:17], v[16:17], s[26:27]
	v_pk_mul_f32 v[18:19], v[18:19], s[26:27]
	v_cvt_pk_bf16_f32 v28, v28, v29
	v_cvt_pk_bf16_f32 v29, v30, v31
	v_cvt_pk_bf16_f32 v30, v24, v25
	v_cvt_pk_bf16_f32 v31, v26, v27
	v_cvt_pk_bf16_f32 v20, v20, v21
	v_cvt_pk_bf16_f32 v21, v22, v23
	v_cvt_pk_bf16_f32 v22, v16, v17
	v_cvt_pk_bf16_f32 v23, v18, v19
	global_store_dwordx4 v162, v[28:31], s[100:101]
	global_store_dwordx4 v162, v[20:23], s[100:101] offset:128
	s_add_u32 s100, s100, 0x4000
	s_addc_u32 s101, s101, 0
	v_pk_mul_f32 v[12:13], v[12:13], v[160:161] op_sel:[0,1] op_sel_hi:[1,1]
	v_pk_mul_f32 v[14:15], v[14:15], v[160:161] op_sel:[0,1] op_sel_hi:[1,1]
	v_pk_mul_f32 v[8:9], v[8:9], v[160:161] op_sel:[0,1] op_sel_hi:[1,1]
	v_pk_mul_f32 v[10:11], v[10:11], v[160:161] op_sel:[0,1] op_sel_hi:[1,1]
	v_pk_mul_f32 v[4:5], v[4:5], v[160:161] op_sel:[0,1] op_sel_hi:[1,1]
	v_pk_mul_f32 v[6:7], v[6:7], v[160:161] op_sel:[0,1] op_sel_hi:[1,1]
	v_pk_mul_f32 v[0:1], v[0:1], v[160:161] op_sel:[0,1] op_sel_hi:[1,1]
	v_pk_mul_f32 v[2:3], v[2:3], v[160:161] op_sel:[0,1] op_sel_hi:[1,1]
	s_waitcnt vmcnt(2)
	v_mul_f32_e32 v236, v4, v187
	v_mul_f32_e32 v237, v12, v187
	v_fma_f32 v12, v12, v186, -v236
	v_fma_f32 v4, v4, v186, v237
	v_mul_f32_e32 v236, v5, v189
	v_mul_f32_e32 v237, v13, v189
	v_fma_f32 v13, v13, v188, -v236
	v_fma_f32 v5, v5, v188, v237
	v_mul_f32_e32 v236, v6, v191
	v_mul_f32_e32 v237, v14, v191
	v_fma_f32 v14, v14, v190, -v236
	v_fma_f32 v6, v6, v190, v237
	v_mul_f32_e32 v236, v7, v193
	v_mul_f32_e32 v237, v15, v193
	v_fma_f32 v15, v15, v192, -v236
	v_fma_f32 v7, v7, v192, v237
	v_mul_f32_e32 v236, v0, v195
	v_mul_f32_e32 v237, v8, v195
	v_fma_f32 v8, v8, v194, -v236
	v_fma_f32 v0, v0, v194, v237
	v_mul_f32_e32 v236, v1, v197
	v_mul_f32_e32 v237, v9, v197
	v_fma_f32 v9, v9, v196, -v236
	v_fma_f32 v1, v1, v196, v237
	v_mul_f32_e32 v236, v2, v199
	v_mul_f32_e32 v237, v10, v199
	v_fma_f32 v10, v10, v198, -v236
	v_fma_f32 v2, v2, v198, v237
	v_mul_f32_e32 v236, v3, v201
	v_mul_f32_e32 v237, v11, v201
	v_fma_f32 v11, v11, v200, -v236
	v_fma_f32 v3, v3, v200, v237
	v_pk_mul_f32 v[12:13], v[12:13], s[26:27]
	v_pk_mul_f32 v[14:15], v[14:15], s[26:27]
	v_pk_mul_f32 v[8:9], v[8:9], s[26:27]
	v_pk_mul_f32 v[10:11], v[10:11], s[26:27]
	v_pk_mul_f32 v[4:5], v[4:5], s[26:27]
	v_pk_mul_f32 v[6:7], v[6:7], s[26:27]
	v_pk_mul_f32 v[0:1], v[0:1], s[26:27]
	v_pk_mul_f32 v[2:3], v[2:3], s[26:27]
	v_cvt_pk_bf16_f32 v12, v12, v13
	v_cvt_pk_bf16_f32 v13, v14, v15
	v_cvt_pk_bf16_f32 v14, v8, v9
	v_cvt_pk_bf16_f32 v15, v10, v11
	v_cvt_pk_bf16_f32 v4, v4, v5
	v_cvt_pk_bf16_f32 v5, v6, v7
	v_cvt_pk_bf16_f32 v6, v0, v1
	v_cvt_pk_bf16_f32 v7, v2, v3
	global_store_dwordx4 v162, v[12:15], s[100:101]
	global_store_dwordx4 v162, v[4:7], s[100:101] offset:128
.Lei_done:
	s_andn2_b64 vcc, exec, s[0:1]
	s_mov_b64 s[0:1], -1
	s_cbranch_vccnz .LBB0_256
.LBB0_360:
	s_andn2_b64 vcc, exec, s[14:15]
	s_cbranch_vccnz .LBB0_255
	s_barrier
	s_branch .LBB0_255
